# GEMM k-loops: s_setprio 1 issued before the merged wait (the wait is followed directly by the barrier)
# baseline (speedup 1.0000x reference)
.LBB0_145:
	s_add_u32 s27, s50, 0x100
	s_addc_u32 s56, s51, 0
	s_mov_b32 s57, -2
	s_waitcnt lgkmcnt(0)
	ds_read_b128 v[128:131], v188
	ds_read_b128 v[132:135], v188 offset:1024
	ds_read_b128 v[136:139], v188 offset:2048
	ds_read_b128 v[140:143], v188 offset:3072
	ds_read_b128 v[144:147], v189
	ds_read_b128 v[148:151], v189 offset:1024
	ds_read_b128 v[176:179], v189 offset:2048
	ds_read_b128 v[180:183], v189 offset:3072
	s_add_u32 s50, s48, 0x100
	s_addc_u32 s51, s49, 0
	s_cmp_eq_u32 s57, 28
	s_cselect_b32 s55, s21, s51
	s_cselect_b32 s54, s20, s50
	s_cselect_b32 s53, s23, s56
	s_cselect_b32 s52, s22, s27
	v_lshl_add_u64 v[184:185], s[48:49], 0, v[170:171]
	s_add_i32 m0, s60, 0xc000
	ds_read_b128 v[194:197], v190
	ds_read_b128 v[198:201], v190 offset:1024
	ds_read_b128 v[202:205], v190 offset:2048
	ds_read_b128 v[206:209], v190 offset:3072
	ds_read_b128 v[210:213], v190 offset:4096
	ds_read_b128 v[214:217], v190 offset:5120
	ds_read_b128 v[218:221], v190 offset:6144
	ds_read_b128 v[222:225], v190 offset:7168
	global_load_lds_dwordx4 v[184:185], off
	v_lshl_add_u64 v[184:185], s[48:49], 0, v[172:173]
	s_add_i32 m0, s60, 0xe000
	s_nop 0
	global_load_lds_dwordx4 v[184:185], off
	s_setprio 1
	s_waitcnt vmcnt(8) lgkmcnt(0)
	s_barrier
	v_mfma_f32_16x16x32_bf16 v[120:123], v[128:131], v[194:197], 0
	v_mfma_f32_16x16x32_bf16 v[124:127], v[136:139], v[194:197], 0
	v_mfma_f32_16x16x32_bf16 v[108:111], v[128:131], v[202:205], 0
	v_mfma_f32_16x16x32_bf16 v[104:107], v[136:139], v[202:205], 0
	v_mfma_f32_16x16x32_bf16 v[92:95], v[128:131], v[210:213], 0
	v_mfma_f32_16x16x32_bf16 v[88:91], v[136:139], v[210:213], 0
	v_mfma_f32_16x16x32_bf16 v[76:79], v[128:131], v[218:221], 0
	v_mfma_f32_16x16x32_bf16 v[72:75], v[136:139], v[218:221], 0
	v_mfma_f32_16x16x32_bf16 v[120:123], v[132:135], v[198:201], v[120:123]
	v_mfma_f32_16x16x32_bf16 v[124:127], v[140:143], v[198:201], v[124:127]
	v_mfma_f32_16x16x32_bf16 v[108:111], v[132:135], v[206:209], v[108:111]
	v_mfma_f32_16x16x32_bf16 v[104:107], v[140:143], v[206:209], v[104:107]
	v_mfma_f32_16x16x32_bf16 v[92:95], v[132:135], v[214:217], v[92:95]
	v_mfma_f32_16x16x32_bf16 v[88:91], v[140:143], v[214:217], v[88:91]
	v_mfma_f32_16x16x32_bf16 v[76:79], v[132:135], v[222:225], v[76:79]
	v_mfma_f32_16x16x32_bf16 v[72:75], v[140:143], v[222:225], v[72:75]
	s_setprio 0
	s_setprio 1
	v_mfma_f32_16x16x32_bf16 v[112:115], v[144:147], v[194:197], 0
	v_mfma_f32_16x16x32_bf16 v[116:119], v[176:179], v[194:197], 0
	v_mfma_f32_16x16x32_bf16 v[100:103], v[144:147], v[202:205], 0
	v_mfma_f32_16x16x32_bf16 v[96:99], v[176:179], v[202:205], 0
	v_mfma_f32_16x16x32_bf16 v[84:87], v[144:147], v[210:213], 0
	v_mfma_f32_16x16x32_bf16 v[80:83], v[176:179], v[210:213], 0
	v_mfma_f32_16x16x32_bf16 v[68:71], v[144:147], v[218:221], 0
	v_mfma_f32_16x16x32_bf16 v[64:67], v[176:179], v[218:221], 0
	v_mfma_f32_16x16x32_bf16 v[112:115], v[148:151], v[198:201], v[112:115]
	v_mfma_f32_16x16x32_bf16 v[116:119], v[180:183], v[198:201], v[116:119]
	v_mfma_f32_16x16x32_bf16 v[100:103], v[148:151], v[206:209], v[100:103]
	v_mfma_f32_16x16x32_bf16 v[96:99], v[180:183], v[206:209], v[96:99]
	v_mfma_f32_16x16x32_bf16 v[84:87], v[148:151], v[214:217], v[84:87]
	v_mfma_f32_16x16x32_bf16 v[80:83], v[180:183], v[214:217], v[80:83]
	v_mfma_f32_16x16x32_bf16 v[68:71], v[148:151], v[222:225], v[68:71]
	v_mfma_f32_16x16x32_bf16 v[64:67], v[180:183], v[222:225], v[64:67]
	s_barrier
	s_setprio 0
	s_add_i32 s48, s71, s3
	v_lshl_add_u64 v[184:185], s[52:53], 0, v[154:155]
	s_mov_b32 m0, s48
	ds_read_b128 v[194:197], v190 offset:16384
	ds_read_b128 v[198:201], v190 offset:17408
	ds_read_b128 v[202:205], v190 offset:18432
	ds_read_b128 v[206:209], v190 offset:19456
	ds_read_b128 v[210:213], v190 offset:20480
	ds_read_b128 v[214:217], v190 offset:21504
	ds_read_b128 v[218:221], v190 offset:22528
	ds_read_b128 v[222:225], v190 offset:23552
	global_load_lds_dwordx4 v[184:185], off
	s_add_i32 m0, s48, 0x2000
	s_add_u32 s48, s52, 0x80000
	v_lshl_add_u64 v[226:227], s[52:53], 0, v[158:159]
	s_addc_u32 s49, s53, 0
	s_add_i32 s58, s72, s3
	global_load_lds_dwordx4 v[226:227], off
	v_lshl_add_u64 v[228:229], s[48:49], 0, v[154:155]
	s_mov_b32 m0, s58
	v_lshl_add_u64 v[230:231], s[54:55], 0, v[156:157]
	global_load_lds_dwordx4 v[228:229], off
	v_lshl_add_u64 v[228:229], s[48:49], 0, v[158:159]
	s_add_i32 m0, s58, 0x2000
	s_nop 0
	global_load_lds_dwordx4 v[228:229], off
	v_lshl_add_u64 v[228:229], s[54:55], 0, v[152:153]
	s_mov_b32 m0, s60
	s_nop 0
	global_load_lds_dwordx4 v[228:229], off
	s_mov_b32 m0, s61
	s_nop 0
	global_load_lds_dwordx4 v[230:231], off
	s_setprio 1
	s_waitcnt vmcnt(8) lgkmcnt(0)
	s_barrier
	v_mfma_f32_16x16x32_bf16 v[60:63], v[128:131], v[194:197], 0
	v_mfma_f32_16x16x32_bf16 v[56:59], v[136:139], v[194:197], 0
	v_mfma_f32_16x16x32_bf16 v[44:47], v[128:131], v[202:205], 0
	v_mfma_f32_16x16x32_bf16 v[40:43], v[136:139], v[202:205], 0
	v_mfma_f32_16x16x32_bf16 v[28:31], v[128:131], v[210:213], 0
	v_mfma_f32_16x16x32_bf16 v[24:27], v[136:139], v[210:213], 0
	v_mfma_f32_16x16x32_bf16 v[12:15], v[128:131], v[218:221], 0
	v_mfma_f32_16x16x32_bf16 v[8:11], v[136:139], v[218:221], 0
	v_mfma_f32_16x16x32_bf16 v[60:63], v[132:135], v[198:201], v[60:63]
	v_mfma_f32_16x16x32_bf16 v[56:59], v[140:143], v[198:201], v[56:59]
	v_mfma_f32_16x16x32_bf16 v[44:47], v[132:135], v[206:209], v[44:47]
	v_mfma_f32_16x16x32_bf16 v[40:43], v[140:143], v[206:209], v[40:43]
	v_mfma_f32_16x16x32_bf16 v[28:31], v[132:135], v[214:217], v[28:31]
	v_mfma_f32_16x16x32_bf16 v[24:27], v[140:143], v[214:217], v[24:27]
	v_mfma_f32_16x16x32_bf16 v[12:15], v[132:135], v[222:225], v[12:15]
	v_mfma_f32_16x16x32_bf16 v[8:11], v[140:143], v[222:225], v[8:11]
	s_setprio 0
	s_setprio 1
	v_mfma_f32_16x16x32_bf16 v[52:55], v[144:147], v[194:197], 0
	v_mfma_f32_16x16x32_bf16 v[48:51], v[176:179], v[194:197], 0
	v_mfma_f32_16x16x32_bf16 v[36:39], v[144:147], v[202:205], 0
	v_mfma_f32_16x16x32_bf16 v[32:35], v[176:179], v[202:205], 0
	v_mfma_f32_16x16x32_bf16 v[20:23], v[144:147], v[210:213], 0
	v_mfma_f32_16x16x32_bf16 v[16:19], v[176:179], v[210:213], 0
	v_mfma_f32_16x16x32_bf16 v[4:7], v[144:147], v[218:221], 0
	v_mfma_f32_16x16x32_bf16 v[0:3], v[176:179], v[218:221], 0
	v_mfma_f32_16x16x32_bf16 v[52:55], v[148:151], v[198:201], v[52:55]
	v_mfma_f32_16x16x32_bf16 v[48:51], v[180:183], v[198:201], v[48:51]
	v_mfma_f32_16x16x32_bf16 v[36:39], v[148:151], v[206:209], v[36:39]
	v_mfma_f32_16x16x32_bf16 v[32:35], v[180:183], v[206:209], v[32:35]
	v_mfma_f32_16x16x32_bf16 v[20:23], v[148:151], v[214:217], v[20:23]
	v_mfma_f32_16x16x32_bf16 v[16:19], v[180:183], v[214:217], v[16:19]
	v_mfma_f32_16x16x32_bf16 v[4:7], v[148:151], v[222:225], v[4:7]
	v_mfma_f32_16x16x32_bf16 v[0:3], v[180:183], v[222:225], v[0:3]
	s_barrier
	s_setprio 0
	s_branch .Lpeel_mid_p1
	s_nop 0
	s_nop 0
	s_nop 0
	s_nop 0
.LBB0_146:
	ds_read_b128 v[128:131], v188
	ds_read_b128 v[132:135], v188 offset:1024
	ds_read_b128 v[136:139], v188 offset:2048
	ds_read_b128 v[140:143], v188 offset:3072
	ds_read_b128 v[144:147], v189
	ds_read_b128 v[148:151], v189 offset:1024
	ds_read_b128 v[176:179], v189 offset:2048
	ds_read_b128 v[180:183], v189 offset:3072
	s_add_u32 s50, s48, 0x100
	s_addc_u32 s51, s49, 0
	s_cmp_eq_u32 s57, 28
	s_cselect_b32 s55, s21, s51
	s_cselect_b32 s54, s20, s50
	s_cselect_b32 s53, s23, s56
	s_cselect_b32 s52, s22, s27
	v_lshl_add_u64 v[184:185], s[48:49], 0, v[170:171]
	s_add_i32 m0, s60, 0xc000
	ds_read_b128 v[194:197], v190
	ds_read_b128 v[198:201], v190 offset:1024
	ds_read_b128 v[202:205], v190 offset:2048
	ds_read_b128 v[206:209], v190 offset:3072
	ds_read_b128 v[210:213], v190 offset:4096
	ds_read_b128 v[214:217], v190 offset:5120
	ds_read_b128 v[218:221], v190 offset:6144
	ds_read_b128 v[222:225], v190 offset:7168
	global_load_lds_dwordx4 v[184:185], off
	v_lshl_add_u64 v[184:185], s[48:49], 0, v[172:173]
	s_add_i32 m0, s60, 0xe000
	s_nop 0
	global_load_lds_dwordx4 v[184:185], off
	s_setprio 1
	s_waitcnt vmcnt(8) lgkmcnt(0)
	s_barrier
	v_mfma_f32_16x16x32_bf16 v[120:123], v[128:131], v[194:197], v[120:123]
	v_mfma_f32_16x16x32_bf16 v[124:127], v[136:139], v[194:197], v[124:127]
	v_mfma_f32_16x16x32_bf16 v[108:111], v[128:131], v[202:205], v[108:111]
	v_mfma_f32_16x16x32_bf16 v[104:107], v[136:139], v[202:205], v[104:107]
	v_mfma_f32_16x16x32_bf16 v[92:95], v[128:131], v[210:213], v[92:95]
	v_mfma_f32_16x16x32_bf16 v[88:91], v[136:139], v[210:213], v[88:91]
	v_mfma_f32_16x16x32_bf16 v[76:79], v[128:131], v[218:221], v[76:79]
	v_mfma_f32_16x16x32_bf16 v[72:75], v[136:139], v[218:221], v[72:75]
	v_mfma_f32_16x16x32_bf16 v[120:123], v[132:135], v[198:201], v[120:123]
	v_mfma_f32_16x16x32_bf16 v[124:127], v[140:143], v[198:201], v[124:127]
	v_mfma_f32_16x16x32_bf16 v[108:111], v[132:135], v[206:209], v[108:111]
	v_mfma_f32_16x16x32_bf16 v[104:107], v[140:143], v[206:209], v[104:107]
	v_mfma_f32_16x16x32_bf16 v[92:95], v[132:135], v[214:217], v[92:95]
	v_mfma_f32_16x16x32_bf16 v[88:91], v[140:143], v[214:217], v[88:91]
	v_mfma_f32_16x16x32_bf16 v[76:79], v[132:135], v[222:225], v[76:79]
	v_mfma_f32_16x16x32_bf16 v[72:75], v[140:143], v[222:225], v[72:75]
	s_setprio 0
	s_setprio 1
	v_mfma_f32_16x16x32_bf16 v[112:115], v[144:147], v[194:197], v[112:115]
	v_mfma_f32_16x16x32_bf16 v[116:119], v[176:179], v[194:197], v[116:119]
	v_mfma_f32_16x16x32_bf16 v[100:103], v[144:147], v[202:205], v[100:103]
	v_mfma_f32_16x16x32_bf16 v[96:99], v[176:179], v[202:205], v[96:99]
	v_mfma_f32_16x16x32_bf16 v[84:87], v[144:147], v[210:213], v[84:87]
	v_mfma_f32_16x16x32_bf16 v[80:83], v[176:179], v[210:213], v[80:83]
	v_mfma_f32_16x16x32_bf16 v[68:71], v[144:147], v[218:221], v[68:71]
	v_mfma_f32_16x16x32_bf16 v[64:67], v[176:179], v[218:221], v[64:67]
	v_mfma_f32_16x16x32_bf16 v[112:115], v[148:151], v[198:201], v[112:115]
	v_mfma_f32_16x16x32_bf16 v[116:119], v[180:183], v[198:201], v[116:119]
	v_mfma_f32_16x16x32_bf16 v[100:103], v[148:151], v[206:209], v[100:103]
	v_mfma_f32_16x16x32_bf16 v[96:99], v[180:183], v[206:209], v[96:99]
	v_mfma_f32_16x16x32_bf16 v[84:87], v[148:151], v[214:217], v[84:87]
	v_mfma_f32_16x16x32_bf16 v[80:83], v[180:183], v[214:217], v[80:83]
	v_mfma_f32_16x16x32_bf16 v[68:71], v[148:151], v[222:225], v[68:71]
	v_mfma_f32_16x16x32_bf16 v[64:67], v[180:183], v[222:225], v[64:67]
	s_barrier
	s_setprio 0
	s_add_i32 s48, s71, s3
	v_lshl_add_u64 v[184:185], s[52:53], 0, v[154:155]
	s_mov_b32 m0, s48
	ds_read_b128 v[194:197], v190 offset:16384
	ds_read_b128 v[198:201], v190 offset:17408
	ds_read_b128 v[202:205], v190 offset:18432
	ds_read_b128 v[206:209], v190 offset:19456
	ds_read_b128 v[210:213], v190 offset:20480
	ds_read_b128 v[214:217], v190 offset:21504
	ds_read_b128 v[218:221], v190 offset:22528
	ds_read_b128 v[222:225], v190 offset:23552
	global_load_lds_dwordx4 v[184:185], off
	s_add_i32 m0, s48, 0x2000
	s_add_u32 s48, s52, 0x80000
	v_lshl_add_u64 v[226:227], s[52:53], 0, v[158:159]
	s_addc_u32 s49, s53, 0
	s_add_i32 s58, s72, s3
	global_load_lds_dwordx4 v[226:227], off
	v_lshl_add_u64 v[228:229], s[48:49], 0, v[154:155]
	s_mov_b32 m0, s58
	v_lshl_add_u64 v[230:231], s[54:55], 0, v[156:157]
	global_load_lds_dwordx4 v[228:229], off
	v_lshl_add_u64 v[228:229], s[48:49], 0, v[158:159]
	s_add_i32 m0, s58, 0x2000
	s_nop 0
	global_load_lds_dwordx4 v[228:229], off
	v_lshl_add_u64 v[228:229], s[54:55], 0, v[152:153]
	s_mov_b32 m0, s60
	s_nop 0
	global_load_lds_dwordx4 v[228:229], off
	s_mov_b32 m0, s61
	s_nop 0
	global_load_lds_dwordx4 v[230:231], off
	s_setprio 1
	s_waitcnt vmcnt(8) lgkmcnt(0)
	s_barrier
	v_mfma_f32_16x16x32_bf16 v[60:63], v[128:131], v[194:197], v[60:63]
	v_mfma_f32_16x16x32_bf16 v[56:59], v[136:139], v[194:197], v[56:59]
	v_mfma_f32_16x16x32_bf16 v[44:47], v[128:131], v[202:205], v[44:47]
	v_mfma_f32_16x16x32_bf16 v[40:43], v[136:139], v[202:205], v[40:43]
	v_mfma_f32_16x16x32_bf16 v[28:31], v[128:131], v[210:213], v[28:31]
	v_mfma_f32_16x16x32_bf16 v[24:27], v[136:139], v[210:213], v[24:27]
	v_mfma_f32_16x16x32_bf16 v[12:15], v[128:131], v[218:221], v[12:15]
	v_mfma_f32_16x16x32_bf16 v[8:11], v[136:139], v[218:221], v[8:11]
	v_mfma_f32_16x16x32_bf16 v[60:63], v[132:135], v[198:201], v[60:63]
	v_mfma_f32_16x16x32_bf16 v[56:59], v[140:143], v[198:201], v[56:59]
	v_mfma_f32_16x16x32_bf16 v[44:47], v[132:135], v[206:209], v[44:47]
	v_mfma_f32_16x16x32_bf16 v[40:43], v[140:143], v[206:209], v[40:43]
	v_mfma_f32_16x16x32_bf16 v[28:31], v[132:135], v[214:217], v[28:31]
	v_mfma_f32_16x16x32_bf16 v[24:27], v[140:143], v[214:217], v[24:27]
	v_mfma_f32_16x16x32_bf16 v[12:15], v[132:135], v[222:225], v[12:15]
	v_mfma_f32_16x16x32_bf16 v[8:11], v[140:143], v[222:225], v[8:11]
	s_setprio 0
	s_setprio 1
	v_mfma_f32_16x16x32_bf16 v[52:55], v[144:147], v[194:197], v[52:55]
	v_mfma_f32_16x16x32_bf16 v[48:51], v[176:179], v[194:197], v[48:51]
	v_mfma_f32_16x16x32_bf16 v[36:39], v[144:147], v[202:205], v[36:39]
	v_mfma_f32_16x16x32_bf16 v[32:35], v[176:179], v[202:205], v[32:35]
	v_mfma_f32_16x16x32_bf16 v[20:23], v[144:147], v[210:213], v[20:23]
	v_mfma_f32_16x16x32_bf16 v[16:19], v[176:179], v[210:213], v[16:19]
	v_mfma_f32_16x16x32_bf16 v[4:7], v[144:147], v[218:221], v[4:7]
	v_mfma_f32_16x16x32_bf16 v[0:3], v[176:179], v[218:221], v[0:3]
	v_mfma_f32_16x16x32_bf16 v[52:55], v[148:151], v[198:201], v[52:55]
	v_mfma_f32_16x16x32_bf16 v[48:51], v[180:183], v[198:201], v[48:51]
	v_mfma_f32_16x16x32_bf16 v[36:39], v[148:151], v[206:209], v[36:39]
	v_mfma_f32_16x16x32_bf16 v[32:35], v[180:183], v[206:209], v[32:35]
	v_mfma_f32_16x16x32_bf16 v[20:23], v[148:151], v[214:217], v[20:23]
	v_mfma_f32_16x16x32_bf16 v[16:19], v[180:183], v[214:217], v[16:19]
	v_mfma_f32_16x16x32_bf16 v[4:7], v[148:151], v[222:225], v[4:7]
	v_mfma_f32_16x16x32_bf16 v[0:3], v[180:183], v[222:225], v[0:3]
	s_barrier
	s_setprio 0
.Lpeel_mid_p1:
	s_add_i32 s58, 0, 0x18000
	s_add_i32 s59, 0, 0x1c000
	v_add_u32_e32 v140, s58, v186
	v_add_u32_e32 v160, s59, v186
	ds_read_b128 v[128:131], v140
	ds_read_b128 v[132:135], v140 offset:1024
	ds_read_b128 v[136:139], v140 offset:2048
	ds_read_b128 v[140:143], v140 offset:3072
	ds_read_b128 v[144:147], v160
	ds_read_b128 v[148:151], v160 offset:1024
	ds_read_b128 v[176:179], v160 offset:2048
	ds_read_b128 v[180:183], v160 offset:3072
	s_add_u32 s48, s54, 0xa0000
	s_addc_u32 s49, s55, 0
	s_mov_b32 m0, s62
	v_lshl_add_u64 v[232:233], s[48:49], 0, v[152:153]
	ds_read_b128 v[194:197], v190 offset:32768
	ds_read_b128 v[198:201], v190 offset:33792
	ds_read_b128 v[202:205], v190 offset:34816
	ds_read_b128 v[206:209], v190 offset:35840
	ds_read_b128 v[210:213], v190 offset:36864
	ds_read_b128 v[214:217], v190 offset:37888
	ds_read_b128 v[218:221], v190 offset:38912
	ds_read_b128 v[222:225], v190 offset:39936
	global_load_lds_dwordx4 v[232:233], off
	v_lshl_add_u64 v[232:233], s[48:49], 0, v[156:157]
	s_mov_b32 m0, s63
	s_nop 0
	global_load_lds_dwordx4 v[232:233], off
	s_setprio 1
	s_waitcnt vmcnt(8) lgkmcnt(0)
	s_barrier
	v_mfma_f32_16x16x32_bf16 v[120:123], v[128:131], v[194:197], v[120:123]
	v_mfma_f32_16x16x32_bf16 v[124:127], v[136:139], v[194:197], v[124:127]
	v_mfma_f32_16x16x32_bf16 v[108:111], v[128:131], v[202:205], v[108:111]
	v_mfma_f32_16x16x32_bf16 v[104:107], v[136:139], v[202:205], v[104:107]
	v_mfma_f32_16x16x32_bf16 v[92:95], v[128:131], v[210:213], v[92:95]
	v_mfma_f32_16x16x32_bf16 v[88:91], v[136:139], v[210:213], v[88:91]
	v_mfma_f32_16x16x32_bf16 v[76:79], v[128:131], v[218:221], v[76:79]
	v_mfma_f32_16x16x32_bf16 v[72:75], v[136:139], v[218:221], v[72:75]
	v_mfma_f32_16x16x32_bf16 v[120:123], v[132:135], v[198:201], v[120:123]
	v_mfma_f32_16x16x32_bf16 v[124:127], v[140:143], v[198:201], v[124:127]
	v_mfma_f32_16x16x32_bf16 v[108:111], v[132:135], v[206:209], v[108:111]
	v_mfma_f32_16x16x32_bf16 v[104:107], v[140:143], v[206:209], v[104:107]
	v_mfma_f32_16x16x32_bf16 v[92:95], v[132:135], v[214:217], v[92:95]
	v_mfma_f32_16x16x32_bf16 v[88:91], v[140:143], v[214:217], v[88:91]
	v_mfma_f32_16x16x32_bf16 v[76:79], v[132:135], v[222:225], v[76:79]
	v_mfma_f32_16x16x32_bf16 v[72:75], v[140:143], v[222:225], v[72:75]
	s_setprio 0
	s_setprio 1
	v_mfma_f32_16x16x32_bf16 v[112:115], v[144:147], v[194:197], v[112:115]
	v_mfma_f32_16x16x32_bf16 v[116:119], v[176:179], v[194:197], v[116:119]
	v_mfma_f32_16x16x32_bf16 v[100:103], v[144:147], v[202:205], v[100:103]
	v_mfma_f32_16x16x32_bf16 v[96:99], v[176:179], v[202:205], v[96:99]
	v_mfma_f32_16x16x32_bf16 v[84:87], v[144:147], v[210:213], v[84:87]
	v_mfma_f32_16x16x32_bf16 v[80:83], v[176:179], v[210:213], v[80:83]
	v_mfma_f32_16x16x32_bf16 v[68:71], v[144:147], v[218:221], v[68:71]
	v_mfma_f32_16x16x32_bf16 v[64:67], v[176:179], v[218:221], v[64:67]
	v_mfma_f32_16x16x32_bf16 v[112:115], v[148:151], v[198:201], v[112:115]
	v_mfma_f32_16x16x32_bf16 v[116:119], v[180:183], v[198:201], v[116:119]
	v_mfma_f32_16x16x32_bf16 v[100:103], v[148:151], v[206:209], v[100:103]
	v_mfma_f32_16x16x32_bf16 v[96:99], v[180:183], v[206:209], v[96:99]
	v_mfma_f32_16x16x32_bf16 v[84:87], v[148:151], v[214:217], v[84:87]
	v_mfma_f32_16x16x32_bf16 v[80:83], v[180:183], v[214:217], v[80:83]
	v_mfma_f32_16x16x32_bf16 v[68:71], v[148:151], v[222:225], v[68:71]
	v_mfma_f32_16x16x32_bf16 v[64:67], v[180:183], v[222:225], v[64:67]
	s_barrier
	s_setprio 0
	s_add_i32 s48, s58, s3
	v_lshl_add_u64 v[184:185], v[184:185], 0, s[14:15]
	s_mov_b32 m0, s48
	ds_read_b128 v[194:197], v190 offset:49152
	ds_read_b128 v[198:201], v190 offset:50176
	ds_read_b128 v[202:205], v190 offset:51200
	ds_read_b128 v[206:209], v190 offset:52224
	ds_read_b128 v[210:213], v190 offset:53248
	ds_read_b128 v[214:217], v190 offset:54272
	ds_read_b128 v[218:221], v190 offset:55296
	ds_read_b128 v[222:225], v190 offset:56320
	global_load_lds_dwordx4 v[184:185], off
	s_add_i32 m0, s48, 0x2000
	s_add_u32 s48, s52, 0x80080
	v_lshl_add_u64 v[184:185], v[226:227], 0, s[14:15]
	s_addc_u32 s49, s53, 0
	s_add_i32 s52, s59, s3
	global_load_lds_dwordx4 v[184:185], off
	v_lshl_add_u64 v[184:185], s[48:49], 0, v[154:155]
	s_mov_b32 m0, s52
	s_nop 0
	global_load_lds_dwordx4 v[184:185], off
	v_lshl_add_u64 v[184:185], s[48:49], 0, v[158:159]
	s_add_i32 m0, s52, 0x2000
	s_nop 0
	global_load_lds_dwordx4 v[184:185], off
	v_lshl_add_u64 v[184:185], v[228:229], 0, s[14:15]
	s_mov_b32 m0, s66
	s_nop 0
	global_load_lds_dwordx4 v[184:185], off
	v_lshl_add_u64 v[184:185], v[230:231], 0, s[14:15]
	s_mov_b32 m0, s67
	s_nop 0
	global_load_lds_dwordx4 v[184:185], off
	s_setprio 1
	s_waitcnt vmcnt(8) lgkmcnt(0)
	s_barrier
	v_mfma_f32_16x16x32_bf16 v[60:63], v[128:131], v[194:197], v[60:63]
	v_mfma_f32_16x16x32_bf16 v[56:59], v[136:139], v[194:197], v[56:59]
	v_mfma_f32_16x16x32_bf16 v[44:47], v[128:131], v[202:205], v[44:47]
	v_mfma_f32_16x16x32_bf16 v[40:43], v[136:139], v[202:205], v[40:43]
	v_mfma_f32_16x16x32_bf16 v[28:31], v[128:131], v[210:213], v[28:31]
	v_mfma_f32_16x16x32_bf16 v[24:27], v[136:139], v[210:213], v[24:27]
	v_mfma_f32_16x16x32_bf16 v[12:15], v[128:131], v[218:221], v[12:15]
	v_mfma_f32_16x16x32_bf16 v[8:11], v[136:139], v[218:221], v[8:11]
	v_mfma_f32_16x16x32_bf16 v[60:63], v[132:135], v[198:201], v[60:63]
	v_mfma_f32_16x16x32_bf16 v[56:59], v[140:143], v[198:201], v[56:59]
	v_mfma_f32_16x16x32_bf16 v[44:47], v[132:135], v[206:209], v[44:47]
	v_mfma_f32_16x16x32_bf16 v[40:43], v[140:143], v[206:209], v[40:43]
	v_mfma_f32_16x16x32_bf16 v[28:31], v[132:135], v[214:217], v[28:31]
	v_mfma_f32_16x16x32_bf16 v[24:27], v[140:143], v[214:217], v[24:27]
	v_mfma_f32_16x16x32_bf16 v[12:15], v[132:135], v[222:225], v[12:15]
	v_mfma_f32_16x16x32_bf16 v[8:11], v[140:143], v[222:225], v[8:11]
	s_setprio 0
	s_setprio 1
	v_mfma_f32_16x16x32_bf16 v[52:55], v[144:147], v[194:197], v[52:55]
	v_mfma_f32_16x16x32_bf16 v[48:51], v[176:179], v[194:197], v[48:51]
	v_mfma_f32_16x16x32_bf16 v[36:39], v[144:147], v[202:205], v[36:39]
	v_mfma_f32_16x16x32_bf16 v[32:35], v[176:179], v[202:205], v[32:35]
	s_add_i32 s57, s57, 2
	v_mfma_f32_16x16x32_bf16 v[20:23], v[144:147], v[210:213], v[20:23]
	s_add_u32 s27, s27, 0x100
	v_mfma_f32_16x16x32_bf16 v[16:19], v[176:179], v[210:213], v[16:19]
	s_addc_u32 s56, s56, 0
	v_mfma_f32_16x16x32_bf16 v[4:7], v[144:147], v[218:221], v[4:7]
	s_cmp_gt_u32 s57, 29
	v_mfma_f32_16x16x32_bf16 v[0:3], v[176:179], v[218:221], v[0:3]
	s_mov_b64 s[48:49], s[50:51]
	v_mfma_f32_16x16x32_bf16 v[52:55], v[148:151], v[198:201], v[52:55]
	v_mfma_f32_16x16x32_bf16 v[48:51], v[180:183], v[198:201], v[48:51]
	v_mfma_f32_16x16x32_bf16 v[36:39], v[148:151], v[206:209], v[36:39]
	v_mfma_f32_16x16x32_bf16 v[32:35], v[180:183], v[206:209], v[32:35]
	v_mfma_f32_16x16x32_bf16 v[20:23], v[148:151], v[214:217], v[20:23]
	v_mfma_f32_16x16x32_bf16 v[16:19], v[180:183], v[214:217], v[16:19]
	v_mfma_f32_16x16x32_bf16 v[4:7], v[148:151], v[222:225], v[4:7]
	v_mfma_f32_16x16x32_bf16 v[0:3], v[180:183], v[222:225], v[0:3]
	s_barrier
	s_setprio 0
	s_cbranch_scc0 .LBB0_146
	s_and_b64 vcc, exec, s[18:19]
	s_cbranch_vccz .LBB0_149
	s_barrier

.LBB0_250:
	ds_read_b128 v[148:151], v142
	ds_read_b128 v[152:155], v142 offset:1024
	ds_read_b128 v[156:159], v142 offset:2048
	ds_read_b128 v[160:163], v142 offset:3072
	ds_read_b128 v[164:167], v143
	ds_read_b128 v[168:171], v143 offset:1024
	ds_read_b128 v[176:179], v143 offset:2048
	ds_read_b128 v[180:183], v143 offset:3072
	s_add_i32 s20, s18, 0xf4f60080
	s_cmp_lg_u32 s52, 28
	s_cselect_b32 s20, s20, 0
	s_add_u32 s22, s2, s20
	s_addc_u32 s23, s3, 0
	s_add_u32 s20, s12, s20
	s_addc_u32 s21, s13, 0
	s_mov_b32 m0, s53
	v_lshl_add_u64 v[172:173], v[138:139], 0, s[18:19]
	ds_read_b128 v[188:191], v144
	ds_read_b128 v[192:195], v144 offset:1024
	ds_read_b128 v[196:199], v144 offset:2048
	ds_read_b128 v[200:203], v144 offset:3072
	ds_read_b128 v[204:207], v144 offset:4096
	ds_read_b128 v[208:211], v144 offset:5120
	ds_read_b128 v[212:215], v144 offset:6144
	ds_read_b128 v[216:219], v144 offset:7168
	global_load_lds_dwordx4 v[172:173], off
	v_lshl_add_u64 v[172:173], v[140:141], 0, s[18:19]
	s_mov_b32 m0, s54
	s_nop 0
	global_load_lds_dwordx4 v[172:173], off
	s_setprio 1
	s_waitcnt vmcnt(8) lgkmcnt(0)
	s_barrier
	v_mfma_f32_16x16x32_bf16 v[124:127], v[148:151], v[188:191], v[124:127]
	v_mfma_f32_16x16x32_bf16 v[120:123], v[156:159], v[188:191], v[120:123]
	v_mfma_f32_16x16x32_bf16 v[116:119], v[148:151], v[196:199], v[116:119]
	v_mfma_f32_16x16x32_bf16 v[112:115], v[156:159], v[196:199], v[112:115]
	v_mfma_f32_16x16x32_bf16 v[100:103], v[148:151], v[204:207], v[100:103]
	v_mfma_f32_16x16x32_bf16 v[96:99], v[156:159], v[204:207], v[96:99]
	v_mfma_f32_16x16x32_bf16 v[84:87], v[148:151], v[212:215], v[84:87]
	v_mfma_f32_16x16x32_bf16 v[80:83], v[156:159], v[212:215], v[80:83]
	v_mfma_f32_16x16x32_bf16 v[124:127], v[152:155], v[192:195], v[124:127]
	v_mfma_f32_16x16x32_bf16 v[120:123], v[160:163], v[192:195], v[120:123]
	v_mfma_f32_16x16x32_bf16 v[116:119], v[152:155], v[200:203], v[116:119]
	v_mfma_f32_16x16x32_bf16 v[112:115], v[160:163], v[200:203], v[112:115]
	v_mfma_f32_16x16x32_bf16 v[100:103], v[152:155], v[208:211], v[100:103]
	v_mfma_f32_16x16x32_bf16 v[96:99], v[160:163], v[208:211], v[96:99]
	v_mfma_f32_16x16x32_bf16 v[84:87], v[152:155], v[216:219], v[84:87]
	v_mfma_f32_16x16x32_bf16 v[80:83], v[160:163], v[216:219], v[80:83]
	s_setprio 0
	s_setprio 1
	v_mfma_f32_16x16x32_bf16 v[108:111], v[164:167], v[188:191], v[108:111]
	v_mfma_f32_16x16x32_bf16 v[104:107], v[176:179], v[188:191], v[104:107]
	v_mfma_f32_16x16x32_bf16 v[92:95], v[164:167], v[196:199], v[92:95]
	v_mfma_f32_16x16x32_bf16 v[88:91], v[176:179], v[196:199], v[88:91]
	v_mfma_f32_16x16x32_bf16 v[76:79], v[164:167], v[204:207], v[76:79]
	v_mfma_f32_16x16x32_bf16 v[72:75], v[176:179], v[204:207], v[72:75]
	v_mfma_f32_16x16x32_bf16 v[68:71], v[164:167], v[212:215], v[68:71]
	v_mfma_f32_16x16x32_bf16 v[64:67], v[176:179], v[212:215], v[64:67]
	v_mfma_f32_16x16x32_bf16 v[108:111], v[168:171], v[192:195], v[108:111]
	v_mfma_f32_16x16x32_bf16 v[104:107], v[180:183], v[192:195], v[104:107]
	v_mfma_f32_16x16x32_bf16 v[92:95], v[168:171], v[200:203], v[92:95]
	v_mfma_f32_16x16x32_bf16 v[88:91], v[180:183], v[200:203], v[88:91]
	v_mfma_f32_16x16x32_bf16 v[76:79], v[168:171], v[208:211], v[76:79]
	v_mfma_f32_16x16x32_bf16 v[72:75], v[180:183], v[208:211], v[72:75]
	v_mfma_f32_16x16x32_bf16 v[68:71], v[168:171], v[216:219], v[68:71]
	v_mfma_f32_16x16x32_bf16 v[64:67], v[180:183], v[216:219], v[64:67]
	s_barrier
	s_setprio 0
	s_mov_b32 m0, s55
	v_lshl_add_u64 v[172:173], s[20:21], 0, v[132:133]
	s_add_u32 s64, s20, 0x80000
	ds_read_b128 v[188:191], v144 offset:16384
	ds_read_b128 v[192:195], v144 offset:17408
	ds_read_b128 v[196:199], v144 offset:18432
	ds_read_b128 v[200:203], v144 offset:19456
	ds_read_b128 v[204:207], v144 offset:20480
	ds_read_b128 v[208:211], v144 offset:21504
	ds_read_b128 v[212:215], v144 offset:22528
	ds_read_b128 v[216:219], v144 offset:23552
	global_load_lds_dwordx4 v[172:173], off
	v_lshl_add_u64 v[184:185], s[20:21], 0, v[128:129]
	s_mov_b32 m0, s56
	s_addc_u32 s65, s21, 0
	global_load_lds_dwordx4 v[184:185], off
	v_lshl_add_u64 v[220:221], s[64:65], 0, v[132:133]
	s_mov_b32 m0, s57
	v_lshl_add_u64 v[222:223], s[22:23], 0, v[130:131]
	global_load_lds_dwordx4 v[220:221], off
	v_lshl_add_u64 v[220:221], s[64:65], 0, v[128:129]
	s_mov_b32 m0, s58
	s_nop 0
	global_load_lds_dwordx4 v[220:221], off
	v_lshl_add_u64 v[220:221], s[22:23], 0, v[134:135]
	s_mov_b32 m0, s1
	s_nop 0
	global_load_lds_dwordx4 v[220:221], off
	s_mov_b32 m0, s26
	s_nop 0
	global_load_lds_dwordx4 v[222:223], off
	s_setprio 1
	s_waitcnt vmcnt(8) lgkmcnt(0)
	s_barrier
	v_mfma_f32_16x16x32_bf16 v[60:63], v[148:151], v[188:191], v[60:63]
	v_mfma_f32_16x16x32_bf16 v[56:59], v[156:159], v[188:191], v[56:59]
	v_mfma_f32_16x16x32_bf16 v[52:55], v[148:151], v[196:199], v[52:55]
	v_mfma_f32_16x16x32_bf16 v[48:51], v[156:159], v[196:199], v[48:51]
	v_mfma_f32_16x16x32_bf16 v[36:39], v[148:151], v[204:207], v[36:39]
	v_mfma_f32_16x16x32_bf16 v[32:35], v[156:159], v[204:207], v[32:35]
	v_mfma_f32_16x16x32_bf16 v[20:23], v[148:151], v[212:215], v[20:23]
	v_mfma_f32_16x16x32_bf16 v[16:19], v[156:159], v[212:215], v[16:19]
	v_mfma_f32_16x16x32_bf16 v[60:63], v[152:155], v[192:195], v[60:63]
	v_mfma_f32_16x16x32_bf16 v[56:59], v[160:163], v[192:195], v[56:59]
	v_mfma_f32_16x16x32_bf16 v[52:55], v[152:155], v[200:203], v[52:55]
	v_mfma_f32_16x16x32_bf16 v[48:51], v[160:163], v[200:203], v[48:51]
	v_mfma_f32_16x16x32_bf16 v[36:39], v[152:155], v[208:211], v[36:39]
	v_mfma_f32_16x16x32_bf16 v[32:35], v[160:163], v[208:211], v[32:35]
	v_mfma_f32_16x16x32_bf16 v[20:23], v[152:155], v[216:219], v[20:23]
	v_mfma_f32_16x16x32_bf16 v[16:19], v[160:163], v[216:219], v[16:19]
	s_setprio 0
	s_setprio 1
	v_mfma_f32_16x16x32_bf16 v[44:47], v[164:167], v[188:191], v[44:47]
	v_mfma_f32_16x16x32_bf16 v[40:43], v[176:179], v[188:191], v[40:43]
	v_mfma_f32_16x16x32_bf16 v[28:31], v[164:167], v[196:199], v[28:31]
	v_mfma_f32_16x16x32_bf16 v[24:27], v[176:179], v[196:199], v[24:27]
	v_mfma_f32_16x16x32_bf16 v[12:15], v[164:167], v[204:207], v[12:15]
	v_mfma_f32_16x16x32_bf16 v[8:11], v[176:179], v[204:207], v[8:11]
	v_mfma_f32_16x16x32_bf16 v[4:7], v[164:167], v[212:215], v[4:7]
	v_mfma_f32_16x16x32_bf16 v[0:3], v[176:179], v[212:215], v[0:3]
	v_mfma_f32_16x16x32_bf16 v[44:47], v[168:171], v[192:195], v[44:47]
	v_mfma_f32_16x16x32_bf16 v[40:43], v[180:183], v[192:195], v[40:43]
	v_mfma_f32_16x16x32_bf16 v[28:31], v[168:171], v[200:203], v[28:31]
	v_mfma_f32_16x16x32_bf16 v[24:27], v[180:183], v[200:203], v[24:27]
	v_mfma_f32_16x16x32_bf16 v[12:15], v[168:171], v[208:211], v[12:15]
	v_mfma_f32_16x16x32_bf16 v[8:11], v[180:183], v[208:211], v[8:11]
	v_mfma_f32_16x16x32_bf16 v[4:7], v[168:171], v[216:219], v[4:7]
	v_mfma_f32_16x16x32_bf16 v[0:3], v[180:183], v[216:219], v[0:3]
	s_barrier
	s_setprio 0
	ds_read_b128 v[148:151], v145
	ds_read_b128 v[152:155], v145 offset:1024
	ds_read_b128 v[156:159], v145 offset:2048
	ds_read_b128 v[160:163], v145 offset:3072
	ds_read_b128 v[164:167], v146
	ds_read_b128 v[168:171], v146 offset:1024
	ds_read_b128 v[176:179], v146 offset:2048
	ds_read_b128 v[180:183], v146 offset:3072
	s_add_u32 s22, s22, 0xa0000
	s_addc_u32 s23, s23, 0
	s_mov_b32 m0, s27
	v_lshl_add_u64 v[224:225], s[22:23], 0, v[134:135]
	ds_read_b128 v[188:191], v144 offset:32768
	ds_read_b128 v[192:195], v144 offset:33792
	ds_read_b128 v[196:199], v144 offset:34816
	ds_read_b128 v[200:203], v144 offset:35840
	ds_read_b128 v[204:207], v144 offset:36864
	ds_read_b128 v[208:211], v144 offset:37888
	ds_read_b128 v[212:215], v144 offset:38912
	ds_read_b128 v[216:219], v144 offset:39936
	global_load_lds_dwordx4 v[224:225], off
	v_lshl_add_u64 v[224:225], s[22:23], 0, v[130:131]
	s_mov_b32 m0, s48
	s_nop 0
	global_load_lds_dwordx4 v[224:225], off
	s_setprio 1
	s_waitcnt vmcnt(8) lgkmcnt(0)
	s_barrier
	v_mfma_f32_16x16x32_bf16 v[124:127], v[148:151], v[188:191], v[124:127]
	v_mfma_f32_16x16x32_bf16 v[120:123], v[156:159], v[188:191], v[120:123]
	v_mfma_f32_16x16x32_bf16 v[116:119], v[148:151], v[196:199], v[116:119]
	v_mfma_f32_16x16x32_bf16 v[112:115], v[156:159], v[196:199], v[112:115]
	v_mfma_f32_16x16x32_bf16 v[100:103], v[148:151], v[204:207], v[100:103]
	v_mfma_f32_16x16x32_bf16 v[96:99], v[156:159], v[204:207], v[96:99]
	v_mfma_f32_16x16x32_bf16 v[84:87], v[148:151], v[212:215], v[84:87]
	v_mfma_f32_16x16x32_bf16 v[80:83], v[156:159], v[212:215], v[80:83]
	v_mfma_f32_16x16x32_bf16 v[124:127], v[152:155], v[192:195], v[124:127]
	v_mfma_f32_16x16x32_bf16 v[120:123], v[160:163], v[192:195], v[120:123]
	v_mfma_f32_16x16x32_bf16 v[116:119], v[152:155], v[200:203], v[116:119]
	v_mfma_f32_16x16x32_bf16 v[112:115], v[160:163], v[200:203], v[112:115]
	v_mfma_f32_16x16x32_bf16 v[100:103], v[152:155], v[208:211], v[100:103]
	v_mfma_f32_16x16x32_bf16 v[96:99], v[160:163], v[208:211], v[96:99]
	v_mfma_f32_16x16x32_bf16 v[84:87], v[152:155], v[216:219], v[84:87]
	v_mfma_f32_16x16x32_bf16 v[80:83], v[160:163], v[216:219], v[80:83]
	s_setprio 0
	s_setprio 1
	v_mfma_f32_16x16x32_bf16 v[108:111], v[164:167], v[188:191], v[108:111]
	v_mfma_f32_16x16x32_bf16 v[104:107], v[176:179], v[188:191], v[104:107]
	v_mfma_f32_16x16x32_bf16 v[92:95], v[164:167], v[196:199], v[92:95]
	v_mfma_f32_16x16x32_bf16 v[88:91], v[176:179], v[196:199], v[88:91]
	v_mfma_f32_16x16x32_bf16 v[76:79], v[164:167], v[204:207], v[76:79]
	v_mfma_f32_16x16x32_bf16 v[72:75], v[176:179], v[204:207], v[72:75]
	v_mfma_f32_16x16x32_bf16 v[68:71], v[164:167], v[212:215], v[68:71]
	v_mfma_f32_16x16x32_bf16 v[64:67], v[176:179], v[212:215], v[64:67]
	v_mfma_f32_16x16x32_bf16 v[108:111], v[168:171], v[192:195], v[108:111]
	v_mfma_f32_16x16x32_bf16 v[104:107], v[180:183], v[192:195], v[104:107]
	v_mfma_f32_16x16x32_bf16 v[92:95], v[168:171], v[200:203], v[92:95]
	v_mfma_f32_16x16x32_bf16 v[88:91], v[180:183], v[200:203], v[88:91]
	v_mfma_f32_16x16x32_bf16 v[76:79], v[168:171], v[208:211], v[76:79]
	v_mfma_f32_16x16x32_bf16 v[72:75], v[180:183], v[208:211], v[72:75]
	v_mfma_f32_16x16x32_bf16 v[68:71], v[168:171], v[216:219], v[68:71]
	v_mfma_f32_16x16x32_bf16 v[64:67], v[180:183], v[216:219], v[64:67]
	s_barrier
	s_setprio 0
	s_mov_b32 m0, s59
	v_lshl_add_u64 v[172:173], v[172:173], 0, s[14:15]
	s_add_u32 s20, s20, 0x80080
	ds_read_b128 v[188:191], v144 offset:49152
	ds_read_b128 v[192:195], v144 offset:50176
	ds_read_b128 v[196:199], v144 offset:51200
	ds_read_b128 v[200:203], v144 offset:52224
	ds_read_b128 v[204:207], v144 offset:53248
	ds_read_b128 v[208:211], v144 offset:54272
	ds_read_b128 v[212:215], v144 offset:55296
	ds_read_b128 v[216:219], v144 offset:56320
	global_load_lds_dwordx4 v[172:173], off
	v_lshl_add_u64 v[172:173], v[184:185], 0, s[14:15]
	s_mov_b32 m0, s60
	s_addc_u32 s21, s21, 0
	global_load_lds_dwordx4 v[172:173], off
	v_lshl_add_u64 v[172:173], s[20:21], 0, v[132:133]
	s_mov_b32 m0, s61
	s_nop 0
	global_load_lds_dwordx4 v[172:173], off
	v_lshl_add_u64 v[172:173], s[20:21], 0, v[128:129]
	s_mov_b32 m0, s62
	s_nop 0
	global_load_lds_dwordx4 v[172:173], off
	v_lshl_add_u64 v[172:173], v[220:221], 0, s[14:15]
	s_mov_b32 m0, s50
	s_nop 0
	global_load_lds_dwordx4 v[172:173], off
	v_lshl_add_u64 v[172:173], v[222:223], 0, s[14:15]
	s_mov_b32 m0, s51
	s_nop 0
	global_load_lds_dwordx4 v[172:173], off
	s_setprio 1
	s_waitcnt vmcnt(8) lgkmcnt(0)
	s_barrier
	v_mfma_f32_16x16x32_bf16 v[60:63], v[148:151], v[188:191], v[60:63]
	v_mfma_f32_16x16x32_bf16 v[56:59], v[156:159], v[188:191], v[56:59]
	v_mfma_f32_16x16x32_bf16 v[52:55], v[148:151], v[196:199], v[52:55]
	v_mfma_f32_16x16x32_bf16 v[48:51], v[156:159], v[196:199], v[48:51]
	v_mfma_f32_16x16x32_bf16 v[36:39], v[148:151], v[204:207], v[36:39]
	v_mfma_f32_16x16x32_bf16 v[32:35], v[156:159], v[204:207], v[32:35]
	v_mfma_f32_16x16x32_bf16 v[20:23], v[148:151], v[212:215], v[20:23]
	v_mfma_f32_16x16x32_bf16 v[16:19], v[156:159], v[212:215], v[16:19]
	v_mfma_f32_16x16x32_bf16 v[60:63], v[152:155], v[192:195], v[60:63]
	v_mfma_f32_16x16x32_bf16 v[56:59], v[160:163], v[192:195], v[56:59]
	v_mfma_f32_16x16x32_bf16 v[52:55], v[152:155], v[200:203], v[52:55]
	v_mfma_f32_16x16x32_bf16 v[48:51], v[160:163], v[200:203], v[48:51]
	v_mfma_f32_16x16x32_bf16 v[36:39], v[152:155], v[208:211], v[36:39]
	v_mfma_f32_16x16x32_bf16 v[32:35], v[160:163], v[208:211], v[32:35]
	v_mfma_f32_16x16x32_bf16 v[20:23], v[152:155], v[216:219], v[20:23]
	v_mfma_f32_16x16x32_bf16 v[16:19], v[160:163], v[216:219], v[16:19]
	s_setprio 0
	s_setprio 1
	v_mfma_f32_16x16x32_bf16 v[44:47], v[164:167], v[188:191], v[44:47]
	v_mfma_f32_16x16x32_bf16 v[40:43], v[176:179], v[188:191], v[40:43]
	v_mfma_f32_16x16x32_bf16 v[28:31], v[164:167], v[196:199], v[28:31]
	v_mfma_f32_16x16x32_bf16 v[24:27], v[176:179], v[196:199], v[24:27]
	v_mfma_f32_16x16x32_bf16 v[12:15], v[164:167], v[204:207], v[12:15]
	v_mfma_f32_16x16x32_bf16 v[8:11], v[176:179], v[204:207], v[8:11]
	v_mfma_f32_16x16x32_bf16 v[4:7], v[164:167], v[212:215], v[4:7]
	v_mfma_f32_16x16x32_bf16 v[0:3], v[176:179], v[212:215], v[0:3]
	v_mfma_f32_16x16x32_bf16 v[44:47], v[168:171], v[192:195], v[44:47]
	v_mfma_f32_16x16x32_bf16 v[40:43], v[180:183], v[192:195], v[40:43]
	v_mfma_f32_16x16x32_bf16 v[28:31], v[168:171], v[200:203], v[28:31]
	v_mfma_f32_16x16x32_bf16 v[24:27], v[180:183], v[200:203], v[24:27]
	v_mfma_f32_16x16x32_bf16 v[12:15], v[168:171], v[208:211], v[12:15]
	v_mfma_f32_16x16x32_bf16 v[8:11], v[180:183], v[208:211], v[8:11]
	v_mfma_f32_16x16x32_bf16 v[4:7], v[168:171], v[216:219], v[4:7]
	v_mfma_f32_16x16x32_bf16 v[0:3], v[180:183], v[216:219], v[0:3]
	s_barrier
	s_setprio 0
	s_add_i32 s52, s52, 2
	s_add_u32 s18, s18, 0x100
	s_addc_u32 s19, s19, 0
	s_cmp_gt_u32 s52, 29
	s_cbranch_scc0 .LBB0_250
	s_cmpk_lt_u32 s24, 0x100
	s_cbranch_scc0 .LBB0_253
	s_barrier

.LBB0_596:
	s_lshl_b32 s98, s56, 3
	s_add_i32 s98, s98, s2
	s_mul_i32 s98, s98, 3
	v_lshl_add_u32 v164, s56, 8, v172
	s_cmp_eq_u32 s87, 3
	v_mad_i64_i32 v[162:163], s[56:57], v164, s77, v[156:157]
	s_cselect_b64 s[62:63], -1, 0
	s_lshl_b32 s56, s2, 8
	s_ashr_i32 s57, s56, 31
	v_lshl_add_u64 v[2:3], s[56:57], 1, v[162:163]
	s_mov_b32 s7, s3
	v_lshl_add_u64 v[2:3], v[2:3], 0, s[6:7]
	v_lshl_add_u64 v[166:167], v[2:3], 0, v[160:161]
	s_add_i32 s7, s88, -2
	s_add_u32 s89, s60, 0x100
	v_mov_b32_e32 v1, v0
	v_ashrrev_i32_e32 v165, 31, v164
	s_addc_u32 s90, s61, 0
	v_lshl_add_u64 v[168:169], s[58:59], 0, v[152:153]
	v_lshl_add_u64 v[170:171], s[58:59], 0, v[154:155]
	s_mov_b32 s64, 0
	s_mov_b64 s[60:61], 0
	s_xor_b64 s[62:63], s[62:63], -1
	v_add_u32_e32 v1, s79, v173
	s_add_i32 s2, s64, 2
	ds_read_b128 v[132:135], v1
	ds_read_b128 v[136:139], v1 offset:1024
	ds_read_b128 v[140:143], v1 offset:2048
	ds_read_b128 v[178:181], v1 offset:3072
	v_add_u32_e32 v1, s80, v173
	s_add_u32 s65, s58, s60
	ds_read_b128 v[182:185], v1
	ds_read_b128 v[188:191], v1 offset:1024
	ds_read_b128 v[192:195], v1 offset:2048
	ds_read_b128 v[196:199], v1 offset:3072
	s_addc_u32 s66, s59, s61
	s_add_u32 s65, s65, 0x100
	s_addc_u32 s66, s66, 0
	s_add_u32 s75, s89, s60
	s_addc_u32 s91, s90, s61
	s_cmp_eq_u32 s7, s64
	s_cselect_b32 s67, s51, s66
	s_cselect_b32 s66, s50, s65
	s_cselect_b32 s65, s53, s91
	s_cselect_b32 s64, s52, s75
	v_lshl_add_u64 v[2:3], v[168:169], 0, s[60:61]
	s_add_i32 m0, s69, 0xc000
	ds_read_b128 v[200:203], v174
	ds_read_b128 v[204:207], v174 offset:1024
	ds_read_b128 v[208:211], v174 offset:2048
	ds_read_b128 v[212:215], v174 offset:3072
	ds_read_b128 v[216:219], v174 offset:4096
	ds_read_b128 v[220:223], v174 offset:5120
	ds_read_b128 v[224:227], v174 offset:6144
	ds_read_b128 v[228:231], v174 offset:7168
	global_load_lds_dwordx4 v[2:3], off
	v_lshl_add_u64 v[2:3], v[170:171], 0, s[60:61]
	s_add_i32 m0, s69, 0xe000
	s_nop 0
	global_load_lds_dwordx4 v[2:3], off
	s_setprio 1
	s_waitcnt vmcnt(8) lgkmcnt(0)
	s_barrier
	v_mfma_f32_16x16x32_bf16 v[128:131], v[132:135], v[200:203], 0
	v_mfma_f32_16x16x32_bf16 v[124:127], v[140:143], v[200:203], 0
	v_mfma_f32_16x16x32_bf16 v[112:115], v[132:135], v[208:211], 0
	v_mfma_f32_16x16x32_bf16 v[108:111], v[140:143], v[208:211], 0
	v_mfma_f32_16x16x32_bf16 v[96:99], v[132:135], v[216:219], 0
	v_mfma_f32_16x16x32_bf16 v[92:95], v[140:143], v[216:219], 0
	v_mfma_f32_16x16x32_bf16 v[80:83], v[132:135], v[224:227], 0
	v_mfma_f32_16x16x32_bf16 v[76:79], v[140:143], v[224:227], 0
	v_mfma_f32_16x16x32_bf16 v[128:131], v[136:139], v[204:207], v[128:131]
	v_mfma_f32_16x16x32_bf16 v[124:127], v[178:181], v[204:207], v[124:127]
	v_mfma_f32_16x16x32_bf16 v[112:115], v[136:139], v[212:215], v[112:115]
	v_mfma_f32_16x16x32_bf16 v[108:111], v[178:181], v[212:215], v[108:111]
	v_mfma_f32_16x16x32_bf16 v[96:99], v[136:139], v[220:223], v[96:99]
	v_mfma_f32_16x16x32_bf16 v[92:95], v[178:181], v[220:223], v[92:95]
	v_mfma_f32_16x16x32_bf16 v[80:83], v[136:139], v[228:231], v[80:83]
	v_mfma_f32_16x16x32_bf16 v[76:79], v[178:181], v[228:231], v[76:79]
	s_setprio 0
	s_setprio 1
	v_mfma_f32_16x16x32_bf16 v[120:123], v[182:185], v[200:203], 0
	v_mfma_f32_16x16x32_bf16 v[116:119], v[192:195], v[200:203], 0
	v_mfma_f32_16x16x32_bf16 v[104:107], v[182:185], v[208:211], 0
	v_mfma_f32_16x16x32_bf16 v[100:103], v[192:195], v[208:211], 0
	v_mfma_f32_16x16x32_bf16 v[88:91], v[182:185], v[216:219], 0
	v_mfma_f32_16x16x32_bf16 v[84:87], v[192:195], v[216:219], 0
	v_mfma_f32_16x16x32_bf16 v[72:75], v[182:185], v[224:227], 0
	v_mfma_f32_16x16x32_bf16 v[68:71], v[192:195], v[224:227], 0
	v_mfma_f32_16x16x32_bf16 v[120:123], v[188:191], v[204:207], v[120:123]
	v_mfma_f32_16x16x32_bf16 v[116:119], v[196:199], v[204:207], v[116:119]
	v_mfma_f32_16x16x32_bf16 v[104:107], v[188:191], v[212:215], v[104:107]
	v_mfma_f32_16x16x32_bf16 v[100:103], v[196:199], v[212:215], v[100:103]
	v_mfma_f32_16x16x32_bf16 v[88:91], v[188:191], v[220:223], v[88:91]
	v_mfma_f32_16x16x32_bf16 v[84:87], v[196:199], v[220:223], v[84:87]
	v_mfma_f32_16x16x32_bf16 v[72:75], v[188:191], v[228:231], v[72:75]
	v_mfma_f32_16x16x32_bf16 v[68:71], v[196:199], v[228:231], v[68:71]
	s_barrier
	s_setprio 0
	s_add_i32 s75, s79, s68
	v_lshl_add_u64 v[232:233], s[64:65], 0, v[148:149]
	s_mov_b32 m0, s75
	ds_read_b128 v[200:203], v174 offset:16384
	ds_read_b128 v[204:207], v174 offset:17408
	ds_read_b128 v[208:211], v174 offset:18432
	ds_read_b128 v[212:215], v174 offset:19456
	ds_read_b128 v[216:219], v174 offset:20480
	ds_read_b128 v[220:223], v174 offset:21504
	ds_read_b128 v[224:227], v174 offset:22528
	ds_read_b128 v[228:231], v174 offset:23552
	global_load_lds_dwordx4 v[232:233], off
	s_add_i32 m0, s75, 0x2000
	s_add_u32 s92, s64, 0xa0000
	v_lshl_add_u64 v[234:235], s[64:65], 0, v[144:145]
	s_addc_u32 s93, s65, 0
	s_add_i32 s75, s80, s68
	global_load_lds_dwordx4 v[234:235], off
	v_lshl_add_u64 v[2:3], s[92:93], 0, v[148:149]
	s_mov_b32 m0, s75
	v_lshl_add_u64 v[236:237], s[66:67], 0, v[150:151]
	global_load_lds_dwordx4 v[2:3], off
	v_lshl_add_u64 v[2:3], s[92:93], 0, v[144:145]
	s_add_i32 m0, s75, 0x2000
	v_lshl_add_u64 v[238:239], s[66:67], 0, v[146:147]
	global_load_lds_dwordx4 v[2:3], off
	s_mov_b32 m0, s69
	s_nop 0
	global_load_lds_dwordx4 v[236:237], off
	s_mov_b32 m0, s70
	s_nop 0
	global_load_lds_dwordx4 v[238:239], off
	s_setprio 1
	s_waitcnt vmcnt(8) lgkmcnt(0)
	s_barrier
	v_mfma_f32_16x16x32_bf16 v[64:67], v[132:135], v[200:203], 0
	v_mfma_f32_16x16x32_bf16 v[60:63], v[140:143], v[200:203], 0
	v_mfma_f32_16x16x32_bf16 v[48:51], v[132:135], v[208:211], 0
	v_mfma_f32_16x16x32_bf16 v[44:47], v[140:143], v[208:211], 0
	v_mfma_f32_16x16x32_bf16 v[32:35], v[132:135], v[216:219], 0
	v_mfma_f32_16x16x32_bf16 v[28:31], v[140:143], v[216:219], 0
	v_mfma_f32_16x16x32_bf16 v[16:19], v[132:135], v[224:227], 0
	v_mfma_f32_16x16x32_bf16 v[12:15], v[140:143], v[224:227], 0
	v_mfma_f32_16x16x32_bf16 v[64:67], v[136:139], v[204:207], v[64:67]
	v_mfma_f32_16x16x32_bf16 v[60:63], v[178:181], v[204:207], v[60:63]
	v_mfma_f32_16x16x32_bf16 v[48:51], v[136:139], v[212:215], v[48:51]
	v_mfma_f32_16x16x32_bf16 v[44:47], v[178:181], v[212:215], v[44:47]
	v_mfma_f32_16x16x32_bf16 v[32:35], v[136:139], v[220:223], v[32:35]
	v_mfma_f32_16x16x32_bf16 v[28:31], v[178:181], v[220:223], v[28:31]
	v_mfma_f32_16x16x32_bf16 v[16:19], v[136:139], v[228:231], v[16:19]
	v_mfma_f32_16x16x32_bf16 v[12:15], v[178:181], v[228:231], v[12:15]
	s_setprio 0
	s_setprio 1
	v_mfma_f32_16x16x32_bf16 v[56:59], v[182:185], v[200:203], 0
	v_mfma_f32_16x16x32_bf16 v[52:55], v[192:195], v[200:203], 0
	v_mfma_f32_16x16x32_bf16 v[40:43], v[182:185], v[208:211], 0
	v_mfma_f32_16x16x32_bf16 v[36:39], v[192:195], v[208:211], 0
	v_mfma_f32_16x16x32_bf16 v[24:27], v[182:185], v[216:219], 0
	v_mfma_f32_16x16x32_bf16 v[20:23], v[192:195], v[216:219], 0
	v_mfma_f32_16x16x32_bf16 v[8:11], v[182:185], v[224:227], 0
	v_mfma_f32_16x16x32_bf16 v[2:5], v[192:195], v[224:227], 0
	v_mfma_f32_16x16x32_bf16 v[56:59], v[188:191], v[204:207], v[56:59]
	v_mfma_f32_16x16x32_bf16 v[52:55], v[196:199], v[204:207], v[52:55]
	v_mfma_f32_16x16x32_bf16 v[40:43], v[188:191], v[212:215], v[40:43]
	v_mfma_f32_16x16x32_bf16 v[36:39], v[196:199], v[212:215], v[36:39]
	v_mfma_f32_16x16x32_bf16 v[24:27], v[188:191], v[220:223], v[24:27]
	v_mfma_f32_16x16x32_bf16 v[20:23], v[196:199], v[220:223], v[20:23]
	v_mfma_f32_16x16x32_bf16 v[8:11], v[188:191], v[228:231], v[8:11]
	v_mfma_f32_16x16x32_bf16 v[2:5], v[196:199], v[228:231], v[2:5]
	s_barrier
	s_setprio 0
	s_branch .Lpeel_mid_p3

.LBB0_599:
	v_add_u32_e32 v1, s79, v173
	s_add_i32 s2, s64, 2
	ds_read_b128 v[132:135], v1
	ds_read_b128 v[136:139], v1 offset:1024
	ds_read_b128 v[140:143], v1 offset:2048
	ds_read_b128 v[178:181], v1 offset:3072
	v_add_u32_e32 v1, s80, v173
	s_add_u32 s65, s58, s60
	ds_read_b128 v[182:185], v1
	ds_read_b128 v[188:191], v1 offset:1024
	ds_read_b128 v[192:195], v1 offset:2048
	ds_read_b128 v[196:199], v1 offset:3072
	s_addc_u32 s66, s59, s61
	s_add_u32 s65, s65, 0x100
	s_addc_u32 s66, s66, 0
	s_add_u32 s75, s89, s60
	s_addc_u32 s91, s90, s61
	s_cmp_eq_u32 s7, s64
	s_cselect_b32 s67, s51, s66
	s_cselect_b32 s66, s50, s65
	s_cselect_b32 s65, s53, s91
	s_cselect_b32 s64, s52, s75
	v_lshl_add_u64 v[2:3], v[168:169], 0, s[60:61]
	s_add_i32 m0, s69, 0xc000
	ds_read_b128 v[200:203], v174
	ds_read_b128 v[204:207], v174 offset:1024
	ds_read_b128 v[208:211], v174 offset:2048
	ds_read_b128 v[212:215], v174 offset:3072
	ds_read_b128 v[216:219], v174 offset:4096
	ds_read_b128 v[220:223], v174 offset:5120
	ds_read_b128 v[224:227], v174 offset:6144
	ds_read_b128 v[228:231], v174 offset:7168
	global_load_lds_dwordx4 v[2:3], off
	v_lshl_add_u64 v[2:3], v[170:171], 0, s[60:61]
	s_add_i32 m0, s69, 0xe000
	s_nop 0
	global_load_lds_dwordx4 v[2:3], off
	s_setprio 1
	s_waitcnt vmcnt(8) lgkmcnt(0)
	s_barrier
	v_mfma_f32_16x16x32_bf16 v[128:131], v[132:135], v[200:203], v[128:131]
	v_mfma_f32_16x16x32_bf16 v[124:127], v[140:143], v[200:203], v[124:127]
	v_mfma_f32_16x16x32_bf16 v[112:115], v[132:135], v[208:211], v[112:115]
	v_mfma_f32_16x16x32_bf16 v[108:111], v[140:143], v[208:211], v[108:111]
	v_mfma_f32_16x16x32_bf16 v[96:99], v[132:135], v[216:219], v[96:99]
	v_mfma_f32_16x16x32_bf16 v[92:95], v[140:143], v[216:219], v[92:95]
	v_mfma_f32_16x16x32_bf16 v[80:83], v[132:135], v[224:227], v[80:83]
	v_mfma_f32_16x16x32_bf16 v[76:79], v[140:143], v[224:227], v[76:79]
	v_mfma_f32_16x16x32_bf16 v[128:131], v[136:139], v[204:207], v[128:131]
	v_mfma_f32_16x16x32_bf16 v[124:127], v[178:181], v[204:207], v[124:127]
	v_mfma_f32_16x16x32_bf16 v[112:115], v[136:139], v[212:215], v[112:115]
	v_mfma_f32_16x16x32_bf16 v[108:111], v[178:181], v[212:215], v[108:111]
	v_mfma_f32_16x16x32_bf16 v[96:99], v[136:139], v[220:223], v[96:99]
	v_mfma_f32_16x16x32_bf16 v[92:95], v[178:181], v[220:223], v[92:95]
	v_mfma_f32_16x16x32_bf16 v[80:83], v[136:139], v[228:231], v[80:83]
	v_mfma_f32_16x16x32_bf16 v[76:79], v[178:181], v[228:231], v[76:79]
	s_setprio 0
	s_setprio 1
	v_mfma_f32_16x16x32_bf16 v[120:123], v[182:185], v[200:203], v[120:123]
	v_mfma_f32_16x16x32_bf16 v[116:119], v[192:195], v[200:203], v[116:119]
	v_mfma_f32_16x16x32_bf16 v[104:107], v[182:185], v[208:211], v[104:107]
	v_mfma_f32_16x16x32_bf16 v[100:103], v[192:195], v[208:211], v[100:103]
	v_mfma_f32_16x16x32_bf16 v[88:91], v[182:185], v[216:219], v[88:91]
	v_mfma_f32_16x16x32_bf16 v[84:87], v[192:195], v[216:219], v[84:87]
	v_mfma_f32_16x16x32_bf16 v[72:75], v[182:185], v[224:227], v[72:75]
	v_mfma_f32_16x16x32_bf16 v[68:71], v[192:195], v[224:227], v[68:71]
	v_mfma_f32_16x16x32_bf16 v[120:123], v[188:191], v[204:207], v[120:123]
	v_mfma_f32_16x16x32_bf16 v[116:119], v[196:199], v[204:207], v[116:119]
	v_mfma_f32_16x16x32_bf16 v[104:107], v[188:191], v[212:215], v[104:107]
	v_mfma_f32_16x16x32_bf16 v[100:103], v[196:199], v[212:215], v[100:103]
	v_mfma_f32_16x16x32_bf16 v[88:91], v[188:191], v[220:223], v[88:91]
	v_mfma_f32_16x16x32_bf16 v[84:87], v[196:199], v[220:223], v[84:87]
	v_mfma_f32_16x16x32_bf16 v[72:75], v[188:191], v[228:231], v[72:75]
	v_mfma_f32_16x16x32_bf16 v[68:71], v[196:199], v[228:231], v[68:71]
	s_barrier
	s_setprio 0
	s_add_i32 s75, s79, s68
	v_lshl_add_u64 v[232:233], s[64:65], 0, v[148:149]
	s_mov_b32 m0, s75
	ds_read_b128 v[200:203], v174 offset:16384
	ds_read_b128 v[204:207], v174 offset:17408
	ds_read_b128 v[208:211], v174 offset:18432
	ds_read_b128 v[212:215], v174 offset:19456
	ds_read_b128 v[216:219], v174 offset:20480
	ds_read_b128 v[220:223], v174 offset:21504
	ds_read_b128 v[224:227], v174 offset:22528
	ds_read_b128 v[228:231], v174 offset:23552
	global_load_lds_dwordx4 v[232:233], off
	s_add_i32 m0, s75, 0x2000
	s_add_u32 s92, s64, 0xa0000
	v_lshl_add_u64 v[234:235], s[64:65], 0, v[144:145]
	s_addc_u32 s93, s65, 0
	s_add_i32 s75, s80, s68
	global_load_lds_dwordx4 v[234:235], off
	v_lshl_add_u64 v[2:3], s[92:93], 0, v[148:149]
	s_mov_b32 m0, s75
	v_lshl_add_u64 v[236:237], s[66:67], 0, v[150:151]
	global_load_lds_dwordx4 v[2:3], off
	v_lshl_add_u64 v[2:3], s[92:93], 0, v[144:145]
	s_add_i32 m0, s75, 0x2000
	v_lshl_add_u64 v[238:239], s[66:67], 0, v[146:147]
	global_load_lds_dwordx4 v[2:3], off
	s_mov_b32 m0, s69
	s_nop 0
	global_load_lds_dwordx4 v[236:237], off
	s_mov_b32 m0, s70
	s_nop 0
	global_load_lds_dwordx4 v[238:239], off
	s_setprio 1
	s_waitcnt vmcnt(8) lgkmcnt(0)
	s_barrier
	v_mfma_f32_16x16x32_bf16 v[64:67], v[132:135], v[200:203], v[64:67]
	v_mfma_f32_16x16x32_bf16 v[60:63], v[140:143], v[200:203], v[60:63]
	v_mfma_f32_16x16x32_bf16 v[48:51], v[132:135], v[208:211], v[48:51]
	v_mfma_f32_16x16x32_bf16 v[44:47], v[140:143], v[208:211], v[44:47]
	v_mfma_f32_16x16x32_bf16 v[32:35], v[132:135], v[216:219], v[32:35]
	v_mfma_f32_16x16x32_bf16 v[28:31], v[140:143], v[216:219], v[28:31]
	v_mfma_f32_16x16x32_bf16 v[16:19], v[132:135], v[224:227], v[16:19]
	v_mfma_f32_16x16x32_bf16 v[12:15], v[140:143], v[224:227], v[12:15]
	v_mfma_f32_16x16x32_bf16 v[64:67], v[136:139], v[204:207], v[64:67]
	v_mfma_f32_16x16x32_bf16 v[60:63], v[178:181], v[204:207], v[60:63]
	v_mfma_f32_16x16x32_bf16 v[48:51], v[136:139], v[212:215], v[48:51]
	v_mfma_f32_16x16x32_bf16 v[44:47], v[178:181], v[212:215], v[44:47]
	v_mfma_f32_16x16x32_bf16 v[32:35], v[136:139], v[220:223], v[32:35]
	v_mfma_f32_16x16x32_bf16 v[28:31], v[178:181], v[220:223], v[28:31]
	v_mfma_f32_16x16x32_bf16 v[16:19], v[136:139], v[228:231], v[16:19]
	v_mfma_f32_16x16x32_bf16 v[12:15], v[178:181], v[228:231], v[12:15]
	s_setprio 0
	s_setprio 1
	v_mfma_f32_16x16x32_bf16 v[56:59], v[182:185], v[200:203], v[56:59]
	v_mfma_f32_16x16x32_bf16 v[52:55], v[192:195], v[200:203], v[52:55]
	v_mfma_f32_16x16x32_bf16 v[40:43], v[182:185], v[208:211], v[40:43]
	v_mfma_f32_16x16x32_bf16 v[36:39], v[192:195], v[208:211], v[36:39]
	v_mfma_f32_16x16x32_bf16 v[24:27], v[182:185], v[216:219], v[24:27]
	v_mfma_f32_16x16x32_bf16 v[20:23], v[192:195], v[216:219], v[20:23]
	v_mfma_f32_16x16x32_bf16 v[8:11], v[182:185], v[224:227], v[8:11]
	v_mfma_f32_16x16x32_bf16 v[2:5], v[192:195], v[224:227], v[4:7]
	v_mfma_f32_16x16x32_bf16 v[56:59], v[188:191], v[204:207], v[56:59]
	v_mfma_f32_16x16x32_bf16 v[52:55], v[196:199], v[204:207], v[52:55]
	v_mfma_f32_16x16x32_bf16 v[40:43], v[188:191], v[212:215], v[40:43]
	v_mfma_f32_16x16x32_bf16 v[36:39], v[196:199], v[212:215], v[36:39]
	v_mfma_f32_16x16x32_bf16 v[24:27], v[188:191], v[220:223], v[24:27]
	v_mfma_f32_16x16x32_bf16 v[20:23], v[196:199], v[220:223], v[20:23]
	v_mfma_f32_16x16x32_bf16 v[8:11], v[188:191], v[228:231], v[8:11]
	v_mfma_f32_16x16x32_bf16 v[2:5], v[196:199], v[228:231], v[2:5]
	s_barrier
	s_setprio 0
.Lpeel_mid_p3:
	s_add_i32 s75, 0, 0x18000
	v_add_u32_e32 v1, s75, v173
	s_add_i32 s91, 0, 0x1c000
	ds_read_b128 v[132:135], v1
	ds_read_b128 v[136:139], v1 offset:1024
	ds_read_b128 v[140:143], v1 offset:2048
	ds_read_b128 v[178:181], v1 offset:3072
	v_add_u32_e32 v1, s91, v173
	ds_read_b128 v[182:185], v1
	ds_read_b128 v[188:191], v1 offset:1024
	ds_read_b128 v[192:195], v1 offset:2048
	ds_read_b128 v[196:199], v1 offset:3072
	s_add_u32 s66, s66, 0xa0000
	s_addc_u32 s67, s67, 0
	s_mov_b32 m0, s71
	v_lshl_add_u64 v[6:7], s[66:67], 0, v[150:151]
	ds_read_b128 v[200:203], v174 offset:32768
	ds_read_b128 v[204:207], v174 offset:33792
	ds_read_b128 v[208:211], v174 offset:34816
	ds_read_b128 v[212:215], v174 offset:35840
	ds_read_b128 v[216:219], v174 offset:36864
	ds_read_b128 v[220:223], v174 offset:37888
	ds_read_b128 v[224:227], v174 offset:38912
	ds_read_b128 v[228:231], v174 offset:39936
	global_load_lds_dwordx4 v[6:7], off
	v_lshl_add_u64 v[6:7], s[66:67], 0, v[146:147]
	s_mov_b32 m0, s72
	s_nop 0
	global_load_lds_dwordx4 v[6:7], off
	s_setprio 1
	s_waitcnt vmcnt(8) lgkmcnt(0)
	s_barrier
	v_mfma_f32_16x16x32_bf16 v[128:131], v[132:135], v[200:203], v[128:131]
	v_mfma_f32_16x16x32_bf16 v[124:127], v[140:143], v[200:203], v[124:127]
	v_mfma_f32_16x16x32_bf16 v[112:115], v[132:135], v[208:211], v[112:115]
	v_mfma_f32_16x16x32_bf16 v[108:111], v[140:143], v[208:211], v[108:111]
	v_mfma_f32_16x16x32_bf16 v[96:99], v[132:135], v[216:219], v[96:99]
	v_mfma_f32_16x16x32_bf16 v[92:95], v[140:143], v[216:219], v[92:95]
	v_mfma_f32_16x16x32_bf16 v[80:83], v[132:135], v[224:227], v[80:83]
	v_mfma_f32_16x16x32_bf16 v[76:79], v[140:143], v[224:227], v[76:79]
	v_mfma_f32_16x16x32_bf16 v[128:131], v[136:139], v[204:207], v[128:131]
	v_mfma_f32_16x16x32_bf16 v[124:127], v[178:181], v[204:207], v[124:127]
	v_mfma_f32_16x16x32_bf16 v[112:115], v[136:139], v[212:215], v[112:115]
	v_mfma_f32_16x16x32_bf16 v[108:111], v[178:181], v[212:215], v[108:111]
	v_mfma_f32_16x16x32_bf16 v[96:99], v[136:139], v[220:223], v[96:99]
	v_mfma_f32_16x16x32_bf16 v[92:95], v[178:181], v[220:223], v[92:95]
	v_mfma_f32_16x16x32_bf16 v[80:83], v[136:139], v[228:231], v[80:83]
	v_mfma_f32_16x16x32_bf16 v[76:79], v[178:181], v[228:231], v[76:79]
	s_setprio 0
	s_setprio 1
	v_mfma_f32_16x16x32_bf16 v[120:123], v[182:185], v[200:203], v[120:123]
	v_mfma_f32_16x16x32_bf16 v[116:119], v[192:195], v[200:203], v[116:119]
	v_mfma_f32_16x16x32_bf16 v[104:107], v[182:185], v[208:211], v[104:107]
	v_mfma_f32_16x16x32_bf16 v[100:103], v[192:195], v[208:211], v[100:103]
	v_mfma_f32_16x16x32_bf16 v[88:91], v[182:185], v[216:219], v[88:91]
	v_mfma_f32_16x16x32_bf16 v[84:87], v[192:195], v[216:219], v[84:87]
	v_mfma_f32_16x16x32_bf16 v[72:75], v[182:185], v[224:227], v[72:75]
	v_mfma_f32_16x16x32_bf16 v[68:71], v[192:195], v[224:227], v[68:71]
	v_mfma_f32_16x16x32_bf16 v[120:123], v[188:191], v[204:207], v[120:123]
	v_mfma_f32_16x16x32_bf16 v[116:119], v[196:199], v[204:207], v[116:119]
	v_mfma_f32_16x16x32_bf16 v[104:107], v[188:191], v[212:215], v[104:107]
	v_mfma_f32_16x16x32_bf16 v[100:103], v[196:199], v[212:215], v[100:103]
	v_mfma_f32_16x16x32_bf16 v[88:91], v[188:191], v[220:223], v[88:91]
	v_mfma_f32_16x16x32_bf16 v[84:87], v[196:199], v[220:223], v[84:87]
	v_mfma_f32_16x16x32_bf16 v[72:75], v[188:191], v[228:231], v[72:75]
	v_mfma_f32_16x16x32_bf16 v[68:71], v[196:199], v[228:231], v[68:71]
	s_barrier
	s_setprio 0
	s_add_i32 s66, s75, s68
	v_lshl_add_u64 v[6:7], v[232:233], 0, s[14:15]
	s_mov_b32 m0, s66
	ds_read_b128 v[200:203], v174 offset:49152
	ds_read_b128 v[204:207], v174 offset:50176
	ds_read_b128 v[208:211], v174 offset:51200
	ds_read_b128 v[212:215], v174 offset:52224
	ds_read_b128 v[216:219], v174 offset:53248
	ds_read_b128 v[220:223], v174 offset:54272
	ds_read_b128 v[224:227], v174 offset:55296
	ds_read_b128 v[228:231], v174 offset:56320
	global_load_lds_dwordx4 v[6:7], off
	s_add_i32 m0, s66, 0x2000
	s_add_u32 s64, s64, 0xa0080
	v_lshl_add_u64 v[6:7], v[234:235], 0, s[14:15]
	s_addc_u32 s65, s65, 0
	s_add_i32 s66, s91, s68
	global_load_lds_dwordx4 v[6:7], off
	v_lshl_add_u64 v[6:7], s[64:65], 0, v[148:149]
	s_mov_b32 m0, s66
	s_nop 0
	global_load_lds_dwordx4 v[6:7], off
	v_lshl_add_u64 v[6:7], s[64:65], 0, v[144:145]
	s_add_i32 m0, s66, 0x2000
	s_nop 0
	global_load_lds_dwordx4 v[6:7], off
	v_lshl_add_u64 v[6:7], v[236:237], 0, s[14:15]
	s_mov_b32 m0, s73
	s_nop 0
	global_load_lds_dwordx4 v[6:7], off
	v_lshl_add_u64 v[6:7], v[238:239], 0, s[14:15]
	s_mov_b32 m0, s76
	s_nop 0
	global_load_lds_dwordx4 v[6:7], off
	s_setprio 1
	s_waitcnt vmcnt(8) lgkmcnt(0)
	s_barrier
	v_mfma_f32_16x16x32_bf16 v[64:67], v[132:135], v[200:203], v[64:67]
	v_mfma_f32_16x16x32_bf16 v[60:63], v[140:143], v[200:203], v[60:63]
	v_mfma_f32_16x16x32_bf16 v[48:51], v[132:135], v[208:211], v[48:51]
	v_mfma_f32_16x16x32_bf16 v[44:47], v[140:143], v[208:211], v[44:47]
	v_mfma_f32_16x16x32_bf16 v[32:35], v[132:135], v[216:219], v[32:35]
	v_mfma_f32_16x16x32_bf16 v[28:31], v[140:143], v[216:219], v[28:31]
	v_mfma_f32_16x16x32_bf16 v[16:19], v[132:135], v[224:227], v[16:19]
	v_mfma_f32_16x16x32_bf16 v[12:15], v[140:143], v[224:227], v[12:15]
	v_mfma_f32_16x16x32_bf16 v[64:67], v[136:139], v[204:207], v[64:67]
	v_mfma_f32_16x16x32_bf16 v[60:63], v[178:181], v[204:207], v[60:63]
	v_mfma_f32_16x16x32_bf16 v[48:51], v[136:139], v[212:215], v[48:51]
	s_add_u32 s60, s60, 0x100
	v_mfma_f32_16x16x32_bf16 v[44:47], v[178:181], v[212:215], v[44:47]
	s_addc_u32 s61, s61, 0
	v_mfma_f32_16x16x32_bf16 v[32:35], v[136:139], v[220:223], v[32:35]
	s_cmp_eq_u32 s2, 16
	v_mfma_f32_16x16x32_bf16 v[28:31], v[178:181], v[220:223], v[28:31]
	s_cselect_b32 s100, 1, 0
	v_mfma_f32_16x16x32_bf16 v[16:19], v[136:139], v[228:231], v[16:19]
	s_cmp_eq_u32 s2, 24
	v_mfma_f32_16x16x32_bf16 v[12:15], v[178:181], v[228:231], v[12:15]
	s_cselect_b32 s101, 1, 0
	s_setprio 0
	s_setprio 1
	v_mfma_f32_16x16x32_bf16 v[56:59], v[182:185], v[200:203], v[56:59]
	s_or_b32 s100, s100, s101
	v_mfma_f32_16x16x32_bf16 v[52:55], v[192:195], v[200:203], v[52:55]
	s_cmp_eq_u64 s[62:63], 0
	v_mfma_f32_16x16x32_bf16 v[40:43], v[182:185], v[208:211], v[40:43]
	s_cselect_b32 s100, s100, 0
	v_mfma_f32_16x16x32_bf16 v[36:39], v[192:195], v[208:211], v[36:39]
	s_cmp_ge_i32 s2, s88
	v_mfma_f32_16x16x32_bf16 v[24:27], v[182:185], v[216:219], v[24:27]
	s_cselect_b32 s67, 1, 0
	v_mfma_f32_16x16x32_bf16 v[20:23], v[192:195], v[216:219], v[20:23]
	s_cmp_eq_u64 s[18:19], 0
	v_mfma_f32_16x16x32_bf16 v[6:9], v[182:185], v[224:227], v[8:11]
	s_cselect_b32 s66, 0, s100
	v_mfma_f32_16x16x32_bf16 v[2:5], v[192:195], v[224:227], v[2:5]
	s_cselect_b32 s100, s100, 0
	v_mfma_f32_16x16x32_bf16 v[56:59], v[188:191], v[204:207], v[56:59]
	s_or_b32 s66, s66, s67
	v_mfma_f32_16x16x32_bf16 v[52:55], v[196:199], v[204:207], v[52:55]
	s_mov_b32 s64, s2
	v_mfma_f32_16x16x32_bf16 v[40:43], v[188:191], v[212:215], v[40:43]
	s_cmp_lg_u32 s100, 0
	v_mfma_f32_16x16x32_bf16 v[36:39], v[196:199], v[212:215], v[36:39]
	v_mfma_f32_16x16x32_bf16 v[24:27], v[188:191], v[220:223], v[24:27]
	v_mfma_f32_16x16x32_bf16 v[20:23], v[196:199], v[220:223], v[20:23]
	v_mfma_f32_16x16x32_bf16 v[8:11], v[188:191], v[228:231], v[6:9]
	v_mfma_f32_16x16x32_bf16 v[4:7], v[196:199], v[228:231], v[2:5]
	s_setprio 0
	s_cbranch_scc0 .Lhk_skipB

.LBB0_671:
	s_add_u32 s6, s6, 0x80080
	s_addc_u32 s7, s7, 0
	s_add_u32 s5, s40, 0x100
	s_addc_u32 s25, s41, 0
	s_mov_b32 s56, -2
	ds_read_b128 v[128:131], v185
	ds_read_b128 v[132:135], v185 offset:1024
	ds_read_b128 v[136:139], v185 offset:2048
	ds_read_b128 v[140:143], v185 offset:3072
	ds_read_b128 v[162:165], v186
	ds_read_b128 v[166:169], v186 offset:1024
	ds_read_b128 v[170:173], v186 offset:2048
	ds_read_b128 v[174:177], v186 offset:3072
	s_add_u32 s38, s6, 0xfff80080
	s_addc_u32 s39, s7, -1
	s_cmp_eq_u32 s56, 28
	s_cselect_b32 s41, s27, s39
	s_cselect_b32 s40, s26, s38
	s_cselect_b32 s39, s23, s25
	s_cselect_b32 s38, s22, s5
	v_lshl_add_u64 v[182:183], s[6:7], 0, v[158:159]
	s_add_i32 m0, s42, 0xc000
	ds_read_b128 v[178:181], v188
	ds_read_b128 v[192:195], v188 offset:1024
	ds_read_b128 v[196:199], v188 offset:2048
	ds_read_b128 v[200:203], v188 offset:3072
	ds_read_b128 v[204:207], v188 offset:4096
	ds_read_b128 v[208:211], v188 offset:5120
	ds_read_b128 v[212:215], v188 offset:6144
	ds_read_b128 v[216:219], v188 offset:7168
	global_load_lds_dwordx4 v[182:183], off
	v_lshl_add_u64 v[182:183], s[6:7], 0, v[160:161]
	s_add_i32 m0, s42, 0xe000
	s_nop 0
	global_load_lds_dwordx4 v[182:183], off
	s_setprio 1
	s_waitcnt vmcnt(8) lgkmcnt(0)
	s_barrier
	v_mfma_f32_16x16x32_bf16 v[124:127], v[128:131], v[178:181], 0
	v_mfma_f32_16x16x32_bf16 v[120:123], v[136:139], v[178:181], 0
	v_mfma_f32_16x16x32_bf16 v[108:111], v[128:131], v[196:199], 0
	v_mfma_f32_16x16x32_bf16 v[104:107], v[136:139], v[196:199], 0
	v_mfma_f32_16x16x32_bf16 v[92:95], v[128:131], v[204:207], 0
	v_mfma_f32_16x16x32_bf16 v[88:91], v[136:139], v[204:207], 0
	v_mfma_f32_16x16x32_bf16 v[76:79], v[128:131], v[212:215], 0
	v_mfma_f32_16x16x32_bf16 v[72:75], v[136:139], v[212:215], 0
	v_mfma_f32_16x16x32_bf16 v[124:127], v[132:135], v[192:195], v[124:127]
	v_mfma_f32_16x16x32_bf16 v[120:123], v[140:143], v[192:195], v[120:123]
	v_mfma_f32_16x16x32_bf16 v[108:111], v[132:135], v[200:203], v[108:111]
	v_mfma_f32_16x16x32_bf16 v[104:107], v[140:143], v[200:203], v[104:107]
	v_mfma_f32_16x16x32_bf16 v[92:95], v[132:135], v[208:211], v[92:95]
	v_mfma_f32_16x16x32_bf16 v[88:91], v[140:143], v[208:211], v[88:91]
	v_mfma_f32_16x16x32_bf16 v[76:79], v[132:135], v[216:219], v[76:79]
	v_mfma_f32_16x16x32_bf16 v[72:75], v[140:143], v[216:219], v[72:75]
	s_setprio 0
	s_setprio 1
	v_mfma_f32_16x16x32_bf16 v[116:119], v[162:165], v[178:181], 0
	v_mfma_f32_16x16x32_bf16 v[112:115], v[170:173], v[178:181], 0
	v_mfma_f32_16x16x32_bf16 v[100:103], v[162:165], v[196:199], 0
	v_mfma_f32_16x16x32_bf16 v[96:99], v[170:173], v[196:199], 0
	v_mfma_f32_16x16x32_bf16 v[84:87], v[162:165], v[204:207], 0
	v_mfma_f32_16x16x32_bf16 v[80:83], v[170:173], v[204:207], 0
	v_mfma_f32_16x16x32_bf16 v[68:71], v[162:165], v[212:215], 0
	v_mfma_f32_16x16x32_bf16 v[64:67], v[170:173], v[212:215], 0
	v_mfma_f32_16x16x32_bf16 v[116:119], v[166:169], v[192:195], v[116:119]
	v_mfma_f32_16x16x32_bf16 v[112:115], v[174:177], v[192:195], v[112:115]
	v_mfma_f32_16x16x32_bf16 v[100:103], v[166:169], v[200:203], v[100:103]
	v_mfma_f32_16x16x32_bf16 v[96:99], v[174:177], v[200:203], v[96:99]
	v_mfma_f32_16x16x32_bf16 v[84:87], v[166:169], v[208:211], v[84:87]
	v_mfma_f32_16x16x32_bf16 v[80:83], v[174:177], v[208:211], v[80:83]
	v_mfma_f32_16x16x32_bf16 v[68:71], v[166:169], v[216:219], v[68:71]
	v_mfma_f32_16x16x32_bf16 v[64:67], v[174:177], v[216:219], v[64:67]
	s_barrier
	s_setprio 0
	s_add_i32 s57, s51, s35
	v_lshl_add_u64 v[182:183], s[38:39], 0, v[148:149]
	s_mov_b32 m0, s57
	ds_read_b128 v[178:181], v188 offset:16384
	ds_read_b128 v[192:195], v188 offset:17408
	ds_read_b128 v[196:199], v188 offset:18432
	ds_read_b128 v[200:203], v188 offset:19456
	ds_read_b128 v[204:207], v188 offset:20480
	ds_read_b128 v[208:211], v188 offset:21504
	ds_read_b128 v[212:215], v188 offset:22528
	ds_read_b128 v[216:219], v188 offset:23552
	global_load_lds_dwordx4 v[182:183], off
	s_add_i32 m0, s57, 0x2000
	s_add_u32 s58, s38, 0x80000
	v_lshl_add_u64 v[220:221], s[38:39], 0, v[144:145]
	s_addc_u32 s59, s39, 0
	s_add_i32 s57, s52, s35
	global_load_lds_dwordx4 v[220:221], off
	v_lshl_add_u64 v[222:223], s[58:59], 0, v[148:149]
	s_mov_b32 m0, s57
	v_lshl_add_u64 v[224:225], s[40:41], 0, v[146:147]
	global_load_lds_dwordx4 v[222:223], off
	v_lshl_add_u64 v[222:223], s[58:59], 0, v[144:145]
	s_add_i32 m0, s57, 0x2000
	s_nop 0
	global_load_lds_dwordx4 v[222:223], off
	v_lshl_add_u64 v[222:223], s[40:41], 0, v[150:151]
	s_mov_b32 m0, s42
	s_nop 0
	global_load_lds_dwordx4 v[222:223], off
	s_mov_b32 m0, s43
	s_nop 0
	global_load_lds_dwordx4 v[224:225], off
	s_setprio 1
	s_waitcnt vmcnt(8) lgkmcnt(0)
	s_barrier
	v_mfma_f32_16x16x32_bf16 v[60:63], v[128:131], v[178:181], 0
	v_mfma_f32_16x16x32_bf16 v[56:59], v[136:139], v[178:181], 0
	v_mfma_f32_16x16x32_bf16 v[44:47], v[128:131], v[196:199], 0
	v_mfma_f32_16x16x32_bf16 v[40:43], v[136:139], v[196:199], 0
	v_mfma_f32_16x16x32_bf16 v[28:31], v[128:131], v[204:207], 0
	v_mfma_f32_16x16x32_bf16 v[24:27], v[136:139], v[204:207], 0
	v_mfma_f32_16x16x32_bf16 v[12:15], v[128:131], v[212:215], 0
	v_mfma_f32_16x16x32_bf16 v[8:11], v[136:139], v[212:215], 0
	v_mfma_f32_16x16x32_bf16 v[60:63], v[132:135], v[192:195], v[60:63]
	v_mfma_f32_16x16x32_bf16 v[56:59], v[140:143], v[192:195], v[56:59]
	v_mfma_f32_16x16x32_bf16 v[44:47], v[132:135], v[200:203], v[44:47]
	v_mfma_f32_16x16x32_bf16 v[40:43], v[140:143], v[200:203], v[40:43]
	v_mfma_f32_16x16x32_bf16 v[28:31], v[132:135], v[208:211], v[28:31]
	v_mfma_f32_16x16x32_bf16 v[24:27], v[140:143], v[208:211], v[24:27]
	v_mfma_f32_16x16x32_bf16 v[12:15], v[132:135], v[216:219], v[12:15]
	v_mfma_f32_16x16x32_bf16 v[8:11], v[140:143], v[216:219], v[8:11]
	s_setprio 0
	s_setprio 1
	v_mfma_f32_16x16x32_bf16 v[52:55], v[162:165], v[178:181], 0
	v_mfma_f32_16x16x32_bf16 v[48:51], v[170:173], v[178:181], 0
	v_mfma_f32_16x16x32_bf16 v[36:39], v[162:165], v[196:199], 0
	v_mfma_f32_16x16x32_bf16 v[32:35], v[170:173], v[196:199], 0
	v_mfma_f32_16x16x32_bf16 v[20:23], v[162:165], v[204:207], 0
	v_mfma_f32_16x16x32_bf16 v[16:19], v[170:173], v[204:207], 0
	v_mfma_f32_16x16x32_bf16 v[4:7], v[162:165], v[212:215], 0
	v_mfma_f32_16x16x32_bf16 v[0:3], v[170:173], v[212:215], 0
	v_mfma_f32_16x16x32_bf16 v[52:55], v[166:169], v[192:195], v[52:55]
	v_mfma_f32_16x16x32_bf16 v[48:51], v[174:177], v[192:195], v[48:51]
	v_mfma_f32_16x16x32_bf16 v[36:39], v[166:169], v[200:203], v[36:39]
	v_mfma_f32_16x16x32_bf16 v[32:35], v[174:177], v[200:203], v[32:35]
	v_mfma_f32_16x16x32_bf16 v[20:23], v[166:169], v[208:211], v[20:23]
	v_mfma_f32_16x16x32_bf16 v[16:19], v[174:177], v[208:211], v[16:19]
	v_mfma_f32_16x16x32_bf16 v[4:7], v[166:169], v[216:219], v[4:7]
	v_mfma_f32_16x16x32_bf16 v[0:3], v[174:177], v[216:219], v[0:3]
	s_barrier
	s_setprio 0
	s_branch .Lpeel_mid_p4
	s_nop 0
	s_nop 0
.LBB0_672:
	ds_read_b128 v[128:131], v185
	ds_read_b128 v[132:135], v185 offset:1024
	ds_read_b128 v[136:139], v185 offset:2048
	ds_read_b128 v[140:143], v185 offset:3072
	ds_read_b128 v[162:165], v186
	ds_read_b128 v[166:169], v186 offset:1024
	ds_read_b128 v[170:173], v186 offset:2048
	ds_read_b128 v[174:177], v186 offset:3072
	s_add_u32 s38, s6, 0xfff80080
	s_addc_u32 s39, s7, -1
	s_cmp_eq_u32 s56, 28
	s_cselect_b32 s41, s27, s39
	s_cselect_b32 s40, s26, s38
	s_cselect_b32 s39, s23, s25
	s_cselect_b32 s38, s22, s5
	v_lshl_add_u64 v[182:183], s[6:7], 0, v[158:159]
	s_add_i32 m0, s42, 0xc000
	ds_read_b128 v[178:181], v188
	ds_read_b128 v[192:195], v188 offset:1024
	ds_read_b128 v[196:199], v188 offset:2048
	ds_read_b128 v[200:203], v188 offset:3072
	ds_read_b128 v[204:207], v188 offset:4096
	ds_read_b128 v[208:211], v188 offset:5120
	ds_read_b128 v[212:215], v188 offset:6144
	ds_read_b128 v[216:219], v188 offset:7168
	global_load_lds_dwordx4 v[182:183], off
	v_lshl_add_u64 v[182:183], s[6:7], 0, v[160:161]
	s_add_i32 m0, s42, 0xe000
	s_nop 0
	global_load_lds_dwordx4 v[182:183], off
	s_setprio 1
	s_waitcnt vmcnt(8) lgkmcnt(0)
	s_barrier
	v_mfma_f32_16x16x32_bf16 v[124:127], v[128:131], v[178:181], v[124:127]
	v_mfma_f32_16x16x32_bf16 v[120:123], v[136:139], v[178:181], v[120:123]
	v_mfma_f32_16x16x32_bf16 v[108:111], v[128:131], v[196:199], v[108:111]
	v_mfma_f32_16x16x32_bf16 v[104:107], v[136:139], v[196:199], v[104:107]
	v_mfma_f32_16x16x32_bf16 v[92:95], v[128:131], v[204:207], v[92:95]
	v_mfma_f32_16x16x32_bf16 v[88:91], v[136:139], v[204:207], v[88:91]
	v_mfma_f32_16x16x32_bf16 v[76:79], v[128:131], v[212:215], v[76:79]
	v_mfma_f32_16x16x32_bf16 v[72:75], v[136:139], v[212:215], v[72:75]
	v_mfma_f32_16x16x32_bf16 v[124:127], v[132:135], v[192:195], v[124:127]
	v_mfma_f32_16x16x32_bf16 v[120:123], v[140:143], v[192:195], v[120:123]
	v_mfma_f32_16x16x32_bf16 v[108:111], v[132:135], v[200:203], v[108:111]
	v_mfma_f32_16x16x32_bf16 v[104:107], v[140:143], v[200:203], v[104:107]
	v_mfma_f32_16x16x32_bf16 v[92:95], v[132:135], v[208:211], v[92:95]
	v_mfma_f32_16x16x32_bf16 v[88:91], v[140:143], v[208:211], v[88:91]
	v_mfma_f32_16x16x32_bf16 v[76:79], v[132:135], v[216:219], v[76:79]
	v_mfma_f32_16x16x32_bf16 v[72:75], v[140:143], v[216:219], v[72:75]
	s_setprio 0
	s_setprio 1
	v_mfma_f32_16x16x32_bf16 v[116:119], v[162:165], v[178:181], v[116:119]
	v_mfma_f32_16x16x32_bf16 v[112:115], v[170:173], v[178:181], v[112:115]
	v_mfma_f32_16x16x32_bf16 v[100:103], v[162:165], v[196:199], v[100:103]
	v_mfma_f32_16x16x32_bf16 v[96:99], v[170:173], v[196:199], v[96:99]
	v_mfma_f32_16x16x32_bf16 v[84:87], v[162:165], v[204:207], v[84:87]
	v_mfma_f32_16x16x32_bf16 v[80:83], v[170:173], v[204:207], v[80:83]
	v_mfma_f32_16x16x32_bf16 v[68:71], v[162:165], v[212:215], v[68:71]
	v_mfma_f32_16x16x32_bf16 v[64:67], v[170:173], v[212:215], v[64:67]
	v_mfma_f32_16x16x32_bf16 v[116:119], v[166:169], v[192:195], v[116:119]
	v_mfma_f32_16x16x32_bf16 v[112:115], v[174:177], v[192:195], v[112:115]
	v_mfma_f32_16x16x32_bf16 v[100:103], v[166:169], v[200:203], v[100:103]
	v_mfma_f32_16x16x32_bf16 v[96:99], v[174:177], v[200:203], v[96:99]
	v_mfma_f32_16x16x32_bf16 v[84:87], v[166:169], v[208:211], v[84:87]
	v_mfma_f32_16x16x32_bf16 v[80:83], v[174:177], v[208:211], v[80:83]
	v_mfma_f32_16x16x32_bf16 v[68:71], v[166:169], v[216:219], v[68:71]
	v_mfma_f32_16x16x32_bf16 v[64:67], v[174:177], v[216:219], v[64:67]
	s_barrier
	s_setprio 0
	s_add_i32 s57, s51, s35
	v_lshl_add_u64 v[182:183], s[38:39], 0, v[148:149]
	s_mov_b32 m0, s57
	ds_read_b128 v[178:181], v188 offset:16384
	ds_read_b128 v[192:195], v188 offset:17408
	ds_read_b128 v[196:199], v188 offset:18432
	ds_read_b128 v[200:203], v188 offset:19456
	ds_read_b128 v[204:207], v188 offset:20480
	ds_read_b128 v[208:211], v188 offset:21504
	ds_read_b128 v[212:215], v188 offset:22528
	ds_read_b128 v[216:219], v188 offset:23552
	global_load_lds_dwordx4 v[182:183], off
	s_add_i32 m0, s57, 0x2000
	s_add_u32 s58, s38, 0x80000
	v_lshl_add_u64 v[220:221], s[38:39], 0, v[144:145]
	s_addc_u32 s59, s39, 0
	s_add_i32 s57, s52, s35
	global_load_lds_dwordx4 v[220:221], off
	v_lshl_add_u64 v[222:223], s[58:59], 0, v[148:149]
	s_mov_b32 m0, s57
	v_lshl_add_u64 v[224:225], s[40:41], 0, v[146:147]
	global_load_lds_dwordx4 v[222:223], off
	v_lshl_add_u64 v[222:223], s[58:59], 0, v[144:145]
	s_add_i32 m0, s57, 0x2000
	s_nop 0
	global_load_lds_dwordx4 v[222:223], off
	v_lshl_add_u64 v[222:223], s[40:41], 0, v[150:151]
	s_mov_b32 m0, s42
	s_nop 0
	global_load_lds_dwordx4 v[222:223], off
	s_mov_b32 m0, s43
	s_nop 0
	global_load_lds_dwordx4 v[224:225], off
	s_setprio 1
	s_waitcnt vmcnt(8) lgkmcnt(0)
	s_barrier
	v_mfma_f32_16x16x32_bf16 v[60:63], v[128:131], v[178:181], v[60:63]
	v_mfma_f32_16x16x32_bf16 v[56:59], v[136:139], v[178:181], v[56:59]
	v_mfma_f32_16x16x32_bf16 v[44:47], v[128:131], v[196:199], v[44:47]
	v_mfma_f32_16x16x32_bf16 v[40:43], v[136:139], v[196:199], v[40:43]
	v_mfma_f32_16x16x32_bf16 v[28:31], v[128:131], v[204:207], v[28:31]
	v_mfma_f32_16x16x32_bf16 v[24:27], v[136:139], v[204:207], v[24:27]
	v_mfma_f32_16x16x32_bf16 v[12:15], v[128:131], v[212:215], v[12:15]
	v_mfma_f32_16x16x32_bf16 v[8:11], v[136:139], v[212:215], v[8:11]
	v_mfma_f32_16x16x32_bf16 v[60:63], v[132:135], v[192:195], v[60:63]
	v_mfma_f32_16x16x32_bf16 v[56:59], v[140:143], v[192:195], v[56:59]
	v_mfma_f32_16x16x32_bf16 v[44:47], v[132:135], v[200:203], v[44:47]
	v_mfma_f32_16x16x32_bf16 v[40:43], v[140:143], v[200:203], v[40:43]
	v_mfma_f32_16x16x32_bf16 v[28:31], v[132:135], v[208:211], v[28:31]
	v_mfma_f32_16x16x32_bf16 v[24:27], v[140:143], v[208:211], v[24:27]
	v_mfma_f32_16x16x32_bf16 v[12:15], v[132:135], v[216:219], v[12:15]
	v_mfma_f32_16x16x32_bf16 v[8:11], v[140:143], v[216:219], v[8:11]
	s_setprio 0
	s_setprio 1
	v_mfma_f32_16x16x32_bf16 v[52:55], v[162:165], v[178:181], v[52:55]
	v_mfma_f32_16x16x32_bf16 v[48:51], v[170:173], v[178:181], v[48:51]
	v_mfma_f32_16x16x32_bf16 v[36:39], v[162:165], v[196:199], v[36:39]
	v_mfma_f32_16x16x32_bf16 v[32:35], v[170:173], v[196:199], v[32:35]
	v_mfma_f32_16x16x32_bf16 v[20:23], v[162:165], v[204:207], v[20:23]
	v_mfma_f32_16x16x32_bf16 v[16:19], v[170:173], v[204:207], v[16:19]
	v_mfma_f32_16x16x32_bf16 v[4:7], v[162:165], v[212:215], v[4:7]
	v_mfma_f32_16x16x32_bf16 v[0:3], v[170:173], v[212:215], v[0:3]
	v_mfma_f32_16x16x32_bf16 v[52:55], v[166:169], v[192:195], v[52:55]
	v_mfma_f32_16x16x32_bf16 v[48:51], v[174:177], v[192:195], v[48:51]
	v_mfma_f32_16x16x32_bf16 v[36:39], v[166:169], v[200:203], v[36:39]
	v_mfma_f32_16x16x32_bf16 v[32:35], v[174:177], v[200:203], v[32:35]
	v_mfma_f32_16x16x32_bf16 v[20:23], v[166:169], v[208:211], v[20:23]
	v_mfma_f32_16x16x32_bf16 v[16:19], v[174:177], v[208:211], v[16:19]
	v_mfma_f32_16x16x32_bf16 v[4:7], v[166:169], v[216:219], v[4:7]
	v_mfma_f32_16x16x32_bf16 v[0:3], v[174:177], v[216:219], v[0:3]
	s_barrier
	s_setprio 0
.Lpeel_mid_p4:
	s_add_i32 s57, 0, 0x18000
	s_add_i32 s58, 0, 0x1c000
	v_add_u32_e32 v140, s57, v184
	v_add_u32_e32 v174, s58, v184
	ds_read_b128 v[128:131], v140
	ds_read_b128 v[132:135], v140 offset:1024
	ds_read_b128 v[136:139], v140 offset:2048
	ds_read_b128 v[140:143], v140 offset:3072
	ds_read_b128 v[162:165], v174
	ds_read_b128 v[166:169], v174 offset:1024
	ds_read_b128 v[170:173], v174 offset:2048
	ds_read_b128 v[174:177], v174 offset:3072
	s_add_u32 s40, s40, 0x80000
	s_addc_u32 s41, s41, 0
	s_mov_b32 m0, s44
	v_lshl_add_u64 v[226:227], s[40:41], 0, v[150:151]
	ds_read_b128 v[178:181], v188 offset:32768
	ds_read_b128 v[192:195], v188 offset:33792
	ds_read_b128 v[196:199], v188 offset:34816
	ds_read_b128 v[200:203], v188 offset:35840
	ds_read_b128 v[204:207], v188 offset:36864
	ds_read_b128 v[208:211], v188 offset:37888
	ds_read_b128 v[212:215], v188 offset:38912
	ds_read_b128 v[216:219], v188 offset:39936
	global_load_lds_dwordx4 v[226:227], off
	v_lshl_add_u64 v[226:227], s[40:41], 0, v[146:147]
	s_mov_b32 m0, s45
	s_nop 0
	global_load_lds_dwordx4 v[226:227], off
	s_setprio 1
	s_waitcnt vmcnt(8) lgkmcnt(0)
	s_barrier
	v_mfma_f32_16x16x32_bf16 v[124:127], v[128:131], v[178:181], v[124:127]
	v_mfma_f32_16x16x32_bf16 v[120:123], v[136:139], v[178:181], v[120:123]
	v_mfma_f32_16x16x32_bf16 v[108:111], v[128:131], v[196:199], v[108:111]
	v_mfma_f32_16x16x32_bf16 v[104:107], v[136:139], v[196:199], v[104:107]
	v_mfma_f32_16x16x32_bf16 v[92:95], v[128:131], v[204:207], v[92:95]
	v_mfma_f32_16x16x32_bf16 v[88:91], v[136:139], v[204:207], v[88:91]
	v_mfma_f32_16x16x32_bf16 v[76:79], v[128:131], v[212:215], v[76:79]
	v_mfma_f32_16x16x32_bf16 v[72:75], v[136:139], v[212:215], v[72:75]
	v_mfma_f32_16x16x32_bf16 v[124:127], v[132:135], v[192:195], v[124:127]
	v_mfma_f32_16x16x32_bf16 v[120:123], v[140:143], v[192:195], v[120:123]
	v_mfma_f32_16x16x32_bf16 v[108:111], v[132:135], v[200:203], v[108:111]
	v_mfma_f32_16x16x32_bf16 v[104:107], v[140:143], v[200:203], v[104:107]
	v_mfma_f32_16x16x32_bf16 v[92:95], v[132:135], v[208:211], v[92:95]
	v_mfma_f32_16x16x32_bf16 v[88:91], v[140:143], v[208:211], v[88:91]
	v_mfma_f32_16x16x32_bf16 v[76:79], v[132:135], v[216:219], v[76:79]
	v_mfma_f32_16x16x32_bf16 v[72:75], v[140:143], v[216:219], v[72:75]
	s_setprio 0
	s_setprio 1
	v_mfma_f32_16x16x32_bf16 v[116:119], v[162:165], v[178:181], v[116:119]
	v_mfma_f32_16x16x32_bf16 v[112:115], v[170:173], v[178:181], v[112:115]
	v_mfma_f32_16x16x32_bf16 v[100:103], v[162:165], v[196:199], v[100:103]
	v_mfma_f32_16x16x32_bf16 v[96:99], v[170:173], v[196:199], v[96:99]
	v_mfma_f32_16x16x32_bf16 v[84:87], v[162:165], v[204:207], v[84:87]
	v_mfma_f32_16x16x32_bf16 v[80:83], v[170:173], v[204:207], v[80:83]
	v_mfma_f32_16x16x32_bf16 v[68:71], v[162:165], v[212:215], v[68:71]
	v_mfma_f32_16x16x32_bf16 v[64:67], v[170:173], v[212:215], v[64:67]
	v_mfma_f32_16x16x32_bf16 v[116:119], v[166:169], v[192:195], v[116:119]
	v_mfma_f32_16x16x32_bf16 v[112:115], v[174:177], v[192:195], v[112:115]
	v_mfma_f32_16x16x32_bf16 v[100:103], v[166:169], v[200:203], v[100:103]
	v_mfma_f32_16x16x32_bf16 v[96:99], v[174:177], v[200:203], v[96:99]
	v_mfma_f32_16x16x32_bf16 v[84:87], v[166:169], v[208:211], v[84:87]
	v_mfma_f32_16x16x32_bf16 v[80:83], v[174:177], v[208:211], v[80:83]
	v_mfma_f32_16x16x32_bf16 v[68:71], v[166:169], v[216:219], v[68:71]
	v_mfma_f32_16x16x32_bf16 v[64:67], v[174:177], v[216:219], v[64:67]
	s_barrier
	s_setprio 0
	s_add_i32 s40, s57, s35
	v_lshl_add_u64 v[182:183], v[182:183], 0, s[14:15]
	s_mov_b32 m0, s40
	ds_read_b128 v[178:181], v188 offset:49152
	ds_read_b128 v[192:195], v188 offset:50176
	ds_read_b128 v[196:199], v188 offset:51200
	ds_read_b128 v[200:203], v188 offset:52224
	ds_read_b128 v[204:207], v188 offset:53248
	ds_read_b128 v[208:211], v188 offset:54272
	ds_read_b128 v[212:215], v188 offset:55296
	ds_read_b128 v[216:219], v188 offset:56320
	global_load_lds_dwordx4 v[182:183], off
	s_add_i32 m0, s40, 0x2000
	s_add_u32 s38, s38, 0x80080
	v_lshl_add_u64 v[182:183], v[220:221], 0, s[14:15]
	s_addc_u32 s39, s39, 0
	s_add_i32 s40, s58, s35
	global_load_lds_dwordx4 v[182:183], off
	v_lshl_add_u64 v[182:183], s[38:39], 0, v[148:149]
	s_mov_b32 m0, s40
	s_nop 0
	global_load_lds_dwordx4 v[182:183], off
	v_lshl_add_u64 v[182:183], s[38:39], 0, v[144:145]
	s_add_i32 m0, s40, 0x2000
	s_nop 0
	global_load_lds_dwordx4 v[182:183], off
	v_lshl_add_u64 v[182:183], v[222:223], 0, s[14:15]
	s_mov_b32 m0, s49
	s_nop 0
	global_load_lds_dwordx4 v[182:183], off
	v_lshl_add_u64 v[182:183], v[224:225], 0, s[14:15]
	s_mov_b32 m0, s50
	s_nop 0
	global_load_lds_dwordx4 v[182:183], off
	s_setprio 1
	s_waitcnt vmcnt(8) lgkmcnt(0)
	s_barrier
	v_mfma_f32_16x16x32_bf16 v[60:63], v[128:131], v[178:181], v[60:63]
	v_mfma_f32_16x16x32_bf16 v[56:59], v[136:139], v[178:181], v[56:59]
	v_mfma_f32_16x16x32_bf16 v[44:47], v[128:131], v[196:199], v[44:47]
	v_mfma_f32_16x16x32_bf16 v[40:43], v[136:139], v[196:199], v[40:43]
	v_mfma_f32_16x16x32_bf16 v[28:31], v[128:131], v[204:207], v[28:31]
	v_mfma_f32_16x16x32_bf16 v[24:27], v[136:139], v[204:207], v[24:27]
	v_mfma_f32_16x16x32_bf16 v[12:15], v[128:131], v[212:215], v[12:15]
	v_mfma_f32_16x16x32_bf16 v[8:11], v[136:139], v[212:215], v[8:11]
	v_mfma_f32_16x16x32_bf16 v[60:63], v[132:135], v[192:195], v[60:63]
	v_mfma_f32_16x16x32_bf16 v[56:59], v[140:143], v[192:195], v[56:59]
	v_mfma_f32_16x16x32_bf16 v[44:47], v[132:135], v[200:203], v[44:47]
	v_mfma_f32_16x16x32_bf16 v[40:43], v[140:143], v[200:203], v[40:43]
	v_mfma_f32_16x16x32_bf16 v[28:31], v[132:135], v[208:211], v[28:31]
	v_mfma_f32_16x16x32_bf16 v[24:27], v[140:143], v[208:211], v[24:27]
	v_mfma_f32_16x16x32_bf16 v[12:15], v[132:135], v[216:219], v[12:15]
	v_mfma_f32_16x16x32_bf16 v[8:11], v[140:143], v[216:219], v[8:11]
	s_setprio 0
	s_setprio 1
	v_mfma_f32_16x16x32_bf16 v[52:55], v[162:165], v[178:181], v[52:55]
	v_mfma_f32_16x16x32_bf16 v[48:51], v[170:173], v[178:181], v[48:51]
	v_mfma_f32_16x16x32_bf16 v[36:39], v[162:165], v[196:199], v[36:39]
	v_mfma_f32_16x16x32_bf16 v[32:35], v[170:173], v[196:199], v[32:35]
	s_add_i32 s56, s56, 2
	v_mfma_f32_16x16x32_bf16 v[20:23], v[162:165], v[204:207], v[20:23]
	s_add_u32 s6, s6, 0x100
	v_mfma_f32_16x16x32_bf16 v[16:19], v[170:173], v[204:207], v[16:19]
	s_addc_u32 s7, s7, 0
	v_mfma_f32_16x16x32_bf16 v[4:7], v[162:165], v[212:215], v[4:7]
	s_add_u32 s5, s5, 0x100
	v_mfma_f32_16x16x32_bf16 v[0:3], v[170:173], v[212:215], v[0:3]
	s_addc_u32 s25, s25, 0
	v_mfma_f32_16x16x32_bf16 v[52:55], v[166:169], v[192:195], v[52:55]
	s_cmp_gt_u32 s56, 29
	v_mfma_f32_16x16x32_bf16 v[48:51], v[174:177], v[192:195], v[48:51]
	v_mfma_f32_16x16x32_bf16 v[36:39], v[166:169], v[200:203], v[36:39]
	v_mfma_f32_16x16x32_bf16 v[32:35], v[174:177], v[200:203], v[32:35]
	v_mfma_f32_16x16x32_bf16 v[20:23], v[166:169], v[208:211], v[20:23]
	v_mfma_f32_16x16x32_bf16 v[16:19], v[174:177], v[208:211], v[16:19]
	v_mfma_f32_16x16x32_bf16 v[4:7], v[166:169], v[216:219], v[4:7]
	v_mfma_f32_16x16x32_bf16 v[0:3], v[174:177], v[216:219], v[0:3]
	s_barrier
	s_setprio 0
	s_cbranch_scc0 .LBB0_672
	s_and_b64 vcc, exec, s[18:19]
	s_cbranch_vccz .LBB0_675
	s_barrier
